# hyena filter loop: paired LDS stores (ds_write2_b32)
# speedup vs baseline: 1.1820x; 1.0041x over previous
; __device__ __forceinline__ void phase_hyena(KP kp_, int hf){ asm volatile("" : "+s"(kp_)); const Params p=load_params(kp_);
;     ...
;       int n=lane&15, kg=lane>>4;
;       f16x8 bw0, bw1;
;       _Pragma("unroll") for (int e=0;e<8;++e){ bw0[e]=(n<4)?(_Float16)misc[(kg*8+e)*4+n]:(_Float16)0.f; bw1[e]=(n<4)?(_Float16)misc[(32+kg*8+e)*4+n]:(_Float16)0.f; }
;       const float dsc=-delta*(1.f/8191.f);
;       float pj0=__expf(dsc*(float)(kg*4)), pj1=__expf(dsc*(float)(kg*4+1)), pj2=__expf(dsc*(float)(kg*4+2)), pj3=__expf(dsc*(float)(kg*4+3));
;       float* Zf=(float*)Z; float ssl=0.f; int order=n&1; bool side1=(n&2)!=0;
;       _Pragma("unroll 8") for (int i=0;i<64;++i){ int tl=wid+8*i;
;         const _Float16* ap=a3+(size_t)(tl*16+n)*64+kg*8;
;         f16x8 a0=*(const f16x8*)ap, a1=*(const f16x8*)(ap+32);
;         f32x4 dd={0.f,0.f,0.f,0.f};
;         dd=__builtin_amdgcn_mfma_f32_16x16x32_f16(a0,bw0,dd,0,0,0);
;         dd=__builtin_amdgcn_mfma_f32_16x16x32_f16(a1,bw1,dd,0,0,0);
;         if (n<4){ float d0=__expf(dsc*(float)(tl*16)); int lag0=tl*16+kg*4;
;           float v0=dd[0]*d0*pj0, v1=dd[1]*d0*pj1, v2=dd[2]*d0*pj2, v3=dd[3]*d0*pj3;
;           if (!side1){ Zf[2*(lag0)+order]=v0; Zf[2*(lag0+1)+order]=v1; Zf[2*(lag0+2)+order]=v2; Zf[2*(lag0+3)+order]=v3; ssl+=v0*v0+v1*v1+v2*v2+v3*v3; }
;           else { if (lag0>=1){ Zf[2*(16384-lag0)+order]=v0; ssl+=v0*v0; }
;             Zf[2*(16384-lag0-1)+order]=v1; Zf[2*(16384-lag0-2)+order]=v2; Zf[2*(16384-lag0-3)+order]=v3; ssl+=v1*v1+v2*v2+v3*v3; } }
;       }
;       ss0=(n<4 && order==0)?ssl:0.f; ss1=(n<4 && order==1)?ssl:0.f;
.LBB0_1232:
	s_or_b64 exec, exec, s[12:13]
	v_perm_b32 v3, v15, v3, s82
	v_perm_b32 v2, v7, v2, s82
	v_perm_b32 v1, v6, v1, s82
	v_perm_b32 v0, v5, v0, s82
	v_perm_b32 v7, v14, v13, s82
	v_perm_b32 v6, v12, v11, s82
	v_perm_b32 v5, v10, v9, s82
	v_perm_b32 v4, v8, v4, s82
	v_and_b32_e32 v222, 63, v154
	v_lshrrev_b32_e32 v29, 6, v154
	v_lshrrev_b32_e32 v223, 2, v222
	v_and_b32_e32 v224, 3, v222
	v_lshlrev_b32_e32 v85, 11, v29
	v_lshl_add_u32 v85, v223, 7, v85
	v_lshl_add_u32 v85, v224, 4, v85
	v_add_u32_e32 v85, 0x3b89000, v85
	global_load_dwordx4 v[228:231], v85, s[70:71]
	global_load_dwordx4 v[232:235], v85, s[70:71] offset:64
	v_add_u32_e32 v85, 0x4000, v85
	global_load_dwordx4 v[236:239], v85, s[70:71]
	global_load_dwordx4 v[240:243], v85, s[70:71] offset:64
	v_add_u32_e32 v85, 0x4000, v85
	global_load_dwordx4 v[244:247], v85, s[70:71]
	global_load_dwordx4 v[248:251], v85, s[70:71] offset:64
	v_add_u32_e32 v85, 0x4000, v85
	v_and_b32_e32 v223, 15, v222
	v_lshrrev_b32_e32 v224, 4, v222
	v_lshlrev_b32_e32 v30, 4, v223
	v_lshl_add_u32 v30, v224, 2, v30
	v_lshlrev_b32_e32 v78, 7, v29
	v_lshl_add_u32 v78, v224, 5, v78
	v_and_b32_e32 v227, 1, v223
	v_lshlrev_b32_e32 v227, 2, v227
	v_sub_u32_e32 v79, 0x1ffe8, v78
	v_add_u32_e32 v78, v78, v227
	v_add_u32_e32 v79, v79, v227
	v_cndmask_b32_e64 v78, v78, v79, s[40:41]
	v_mov_b32_e32 v227, 0x400
	v_mov_b32_e32 v79, 0xfffffc00
	v_cndmask_b32_e64 v79, v227, v79, s[40:41]
	v_cndmask_b32_e64 v80, v95, v50, s[40:41]
	v_cndmask_b32_e64 v81, v51, v96, s[40:41]
	v_cndmask_b32_e64 v82, v96, v51, s[40:41]
	v_cndmask_b32_e64 v84, v50, v95, s[40:41]
	v_lshrrev_b32_e32 v227, 4, v154
	v_cmp_eq_u32_e64 s[100:101], 0, v227
	s_nop 3
	s_and_b64 s[100:101], s[100:101], s[40:41]
	s_and_b64 s[100:101], s[100:101], s[38:39]
	s_andn2_b64 s[100:101], s[38:39], s[100:101]
	v_lshlrev_b32_e32 v29, 4, v29
	v_mov_b32_e32 v28, 0
	s_waitcnt vmcnt(4)
	ds_bpermute_b32 v12, v30, v228
	ds_bpermute_b32 v13, v30, v229
	ds_bpermute_b32 v14, v30, v230
	ds_bpermute_b32 v15, v30, v231
	ds_bpermute_b32 v16, v30, v232
	ds_bpermute_b32 v17, v30, v233
	ds_bpermute_b32 v18, v30, v234
	ds_bpermute_b32 v19, v30, v235
	global_load_dwordx4 v[228:231], v85, s[70:71]
	global_load_dwordx4 v[232:235], v85, s[70:71] offset:64
	v_add_u32_e32 v85, 0x4000, v85
	s_waitcnt vmcnt(4)
	ds_bpermute_b32 v20, v30, v236
	ds_bpermute_b32 v21, v30, v237
	ds_bpermute_b32 v22, v30, v238
	ds_bpermute_b32 v23, v30, v239
	ds_bpermute_b32 v24, v30, v240
	ds_bpermute_b32 v25, v30, v241
	ds_bpermute_b32 v26, v30, v242
	ds_bpermute_b32 v27, v30, v243
	global_load_dwordx4 v[236:239], v85, s[70:71]
	global_load_dwordx4 v[240:243], v85, s[70:71] offset:64
	v_add_u32_e32 v85, 0x4000, v85
	v_mov_b32_e32 v227, v29
	v_cvt_f32_i32_e32 v227, v227
	v_mul_f32_e32 v227, v93, v227
	v_mul_f32_e32 v227, 0x3fb8aa3b, v227
	v_exp_f32_e32 v226, v227
	s_waitcnt lgkmcnt(8)
	v_mfma_f32_16x16x32_f16 v[8:11], v[12:15], v[0:3], 0
	v_mfma_f32_16x16x32_f16 v[8:11], v[16:19], v[4:7], v[8:11]
	s_nop 7
	v_cndmask_b32_e64 v222, v8, v11, s[40:41]
	v_cndmask_b32_e64 v223, v9, v10, s[40:41]
	v_cndmask_b32_e64 v224, v10, v9, s[40:41]
	v_cndmask_b32_e64 v225, v11, v8, s[40:41]
	v_mul_f32_e32 v222, v222, v226
	v_mul_f32_e32 v223, v223, v226
	v_mul_f32_e32 v224, v224, v226
	v_mul_f32_e32 v225, v225, v226
	v_mul_f32_e32 v222, v80, v222
	v_mul_f32_e32 v223, v81, v223
	v_mul_f32_e32 v224, v82, v224
	v_mul_f32_e32 v225, v84, v225
	v_mul_f32_e32 v31, v222, v222
	v_fmac_f32_e32 v31, v223, v223
	v_fmac_f32_e32 v31, v224, v224
	v_cndmask_b32_e64 v227, 0, v225, s[100:101]
	v_fmac_f32_e32 v31, v227, v227
	v_add_f32_e32 v28, v28, v31
	s_mov_b64 exec, s[38:39]
	ds_write2_b32 v78, v222, v223 offset1:2
	ds_write_b32 v78, v224 offset:16
	s_mov_b64 exec, s[100:101]
	ds_write_b32 v78, v225 offset:24
	s_mov_b64 exec, -1
	v_add_u32_e32 v78, v78, v79
	s_waitcnt vmcnt(4)
	ds_bpermute_b32 v12, v30, v244
	ds_bpermute_b32 v13, v30, v245
	ds_bpermute_b32 v14, v30, v246
	ds_bpermute_b32 v15, v30, v247
	ds_bpermute_b32 v16, v30, v248
	ds_bpermute_b32 v17, v30, v249
	ds_bpermute_b32 v18, v30, v250
	ds_bpermute_b32 v19, v30, v251
	global_load_dwordx4 v[244:247], v85, s[70:71]
	global_load_dwordx4 v[248:251], v85, s[70:71] offset:64
	v_add_u32_e32 v85, 0x4000, v85
	v_add_u32_e32 v227, 0x80, v29
	v_cvt_f32_i32_e32 v227, v227
	v_mul_f32_e32 v227, v93, v227
	v_mul_f32_e32 v227, 0x3fb8aa3b, v227
	v_exp_f32_e32 v226, v227
	s_waitcnt lgkmcnt(11)
	v_mfma_f32_16x16x32_f16 v[8:11], v[20:23], v[0:3], 0
	v_mfma_f32_16x16x32_f16 v[8:11], v[24:27], v[4:7], v[8:11]
	s_nop 7
	v_cndmask_b32_e64 v222, v8, v11, s[40:41]
	v_cndmask_b32_e64 v223, v9, v10, s[40:41]
	v_cndmask_b32_e64 v224, v10, v9, s[40:41]
	v_cndmask_b32_e64 v225, v11, v8, s[40:41]
	v_mul_f32_e32 v222, v222, v226
	v_mul_f32_e32 v223, v223, v226
	v_mul_f32_e32 v224, v224, v226
	v_mul_f32_e32 v225, v225, v226
	v_mul_f32_e32 v222, v80, v222
	v_mul_f32_e32 v223, v81, v223
	v_mul_f32_e32 v224, v82, v224
	v_mul_f32_e32 v225, v84, v225
	v_mul_f32_e32 v31, v222, v222
	v_fmac_f32_e32 v31, v223, v223
	v_fmac_f32_e32 v31, v224, v224
	v_fmac_f32_e32 v31, v225, v225
	v_add_f32_e32 v28, v28, v31
	s_mov_b64 exec, s[38:39]
	ds_write2_b32 v78, v222, v223 offset1:2
	ds_write2_b32 v78, v224, v225 offset0:4 offset1:6
	s_mov_b64 exec, -1
	v_add_u32_e32 v78, v78, v79
	s_waitcnt vmcnt(4)
	ds_bpermute_b32 v20, v30, v228
	ds_bpermute_b32 v21, v30, v229
	ds_bpermute_b32 v22, v30, v230
	ds_bpermute_b32 v23, v30, v231
	ds_bpermute_b32 v24, v30, v232
	ds_bpermute_b32 v25, v30, v233
	ds_bpermute_b32 v26, v30, v234
	ds_bpermute_b32 v27, v30, v235
	global_load_dwordx4 v[228:231], v85, s[70:71]
	global_load_dwordx4 v[232:235], v85, s[70:71] offset:64
	v_add_u32_e32 v85, 0x4000, v85
	v_add_u32_e32 v227, 0x100, v29
	v_cvt_f32_i32_e32 v227, v227
	v_mul_f32_e32 v227, v93, v227
	v_mul_f32_e32 v227, 0x3fb8aa3b, v227
	v_exp_f32_e32 v226, v227
	s_waitcnt lgkmcnt(10)
; __device__ __forceinline__ void phase_hyena(KP kp_, int hf){ asm volatile("" : "+s"(kp_)); const Params p=load_params(kp_);
;     ...
;       _Pragma("unroll 8") for (int i=0;i<64;++i){ int tl=wid+8*i;
;         const _Float16* ap=a3+(size_t)(tl*16+n)*64+kg*8;
;         f16x8 a0=*(const f16x8*)ap, a1=*(const f16x8*)(ap+32);
;         f32x4 dd={0.f,0.f,0.f,0.f};
;         dd=__builtin_amdgcn_mfma_f32_16x16x32_f16(a0,bw0,dd,0,0,0);
;         dd=__builtin_amdgcn_mfma_f32_16x16x32_f16(a1,bw1,dd,0,0,0);
;         if (n<4){ float d0=__expf(dsc*(float)(tl*16)); int lag0=tl*16+kg*4;
;           float v0=dd[0]*d0*pj0, v1=dd[1]*d0*pj1, v2=dd[2]*d0*pj2, v3=dd[3]*d0*pj3;
;           if (!side1){ Zf[2*(lag0)+order]=v0; Zf[2*(lag0+1)+order]=v1; Zf[2*(lag0+2)+order]=v2; Zf[2*(lag0+3)+order]=v3; ssl+=v0*v0+v1*v1+v2*v2+v3*v3; }
;           else { if (lag0>=1){ Zf[2*(16384-lag0)+order]=v0; ssl+=v0*v0; }
;             Zf[2*(16384-lag0-1)+order]=v1; Zf[2*(16384-lag0-2)+order]=v2; Zf[2*(16384-lag0-3)+order]=v3; ssl+=v1*v1+v2*v2+v3*v3; } }
;       }
	v_mfma_f32_16x16x32_f16 v[8:11], v[12:15], v[0:3], 0
	v_mfma_f32_16x16x32_f16 v[8:11], v[16:19], v[4:7], v[8:11]
	s_nop 7
	v_cndmask_b32_e64 v222, v8, v11, s[40:41]
	v_cndmask_b32_e64 v223, v9, v10, s[40:41]
	v_cndmask_b32_e64 v224, v10, v9, s[40:41]
	v_cndmask_b32_e64 v225, v11, v8, s[40:41]
	v_mul_f32_e32 v222, v222, v226
	v_mul_f32_e32 v223, v223, v226
	v_mul_f32_e32 v224, v224, v226
	v_mul_f32_e32 v225, v225, v226
	v_mul_f32_e32 v222, v80, v222
	v_mul_f32_e32 v223, v81, v223
	v_mul_f32_e32 v224, v82, v224
	v_mul_f32_e32 v225, v84, v225
	v_mul_f32_e32 v31, v222, v222
	v_fmac_f32_e32 v31, v223, v223
	v_fmac_f32_e32 v31, v224, v224
	v_fmac_f32_e32 v31, v225, v225
	v_add_f32_e32 v28, v28, v31
	s_mov_b64 exec, s[38:39]
	ds_write2_b32 v78, v222, v223 offset1:2
	ds_write2_b32 v78, v224, v225 offset0:4 offset1:6
	s_mov_b64 exec, -1
	v_add_u32_e32 v78, v78, v79
	s_waitcnt vmcnt(4)
	ds_bpermute_b32 v12, v30, v236
	ds_bpermute_b32 v13, v30, v237
	ds_bpermute_b32 v14, v30, v238
	ds_bpermute_b32 v15, v30, v239
	ds_bpermute_b32 v16, v30, v240
	ds_bpermute_b32 v17, v30, v241
	ds_bpermute_b32 v18, v30, v242
	ds_bpermute_b32 v19, v30, v243
	global_load_dwordx4 v[236:239], v85, s[70:71]
	global_load_dwordx4 v[240:243], v85, s[70:71] offset:64
	v_add_u32_e32 v85, 0x4000, v85
	v_add_u32_e32 v227, 0x180, v29
	v_cvt_f32_i32_e32 v227, v227
	v_mul_f32_e32 v227, v93, v227
	v_mul_f32_e32 v227, 0x3fb8aa3b, v227
	v_exp_f32_e32 v226, v227
	s_waitcnt lgkmcnt(10)
	v_mfma_f32_16x16x32_f16 v[8:11], v[20:23], v[0:3], 0
	v_mfma_f32_16x16x32_f16 v[8:11], v[24:27], v[4:7], v[8:11]
	s_nop 7
	v_cndmask_b32_e64 v222, v8, v11, s[40:41]
	v_cndmask_b32_e64 v223, v9, v10, s[40:41]
	v_cndmask_b32_e64 v224, v10, v9, s[40:41]
	v_cndmask_b32_e64 v225, v11, v8, s[40:41]
	v_mul_f32_e32 v222, v222, v226
	v_mul_f32_e32 v223, v223, v226
	v_mul_f32_e32 v224, v224, v226
	v_mul_f32_e32 v225, v225, v226
	v_mul_f32_e32 v222, v80, v222
	v_mul_f32_e32 v223, v81, v223
	v_mul_f32_e32 v224, v82, v224
	v_mul_f32_e32 v225, v84, v225
	v_mul_f32_e32 v31, v222, v222
	v_fmac_f32_e32 v31, v223, v223
	v_fmac_f32_e32 v31, v224, v224
	v_fmac_f32_e32 v31, v225, v225
	v_add_f32_e32 v28, v28, v31
	s_mov_b64 exec, s[38:39]
	ds_write2_b32 v78, v222, v223 offset1:2
	ds_write2_b32 v78, v224, v225 offset0:4 offset1:6
	s_mov_b64 exec, -1
	v_add_u32_e32 v78, v78, v79
	s_waitcnt vmcnt(4)
	ds_bpermute_b32 v20, v30, v244
	ds_bpermute_b32 v21, v30, v245
	ds_bpermute_b32 v22, v30, v246
	ds_bpermute_b32 v23, v30, v247
	ds_bpermute_b32 v24, v30, v248
	ds_bpermute_b32 v25, v30, v249
	ds_bpermute_b32 v26, v30, v250
	ds_bpermute_b32 v27, v30, v251
	global_load_dwordx4 v[244:247], v85, s[70:71]
	global_load_dwordx4 v[248:251], v85, s[70:71] offset:64
	v_add_u32_e32 v85, 0x4000, v85
	v_add_u32_e32 v227, 0x200, v29
	v_cvt_f32_i32_e32 v227, v227
	v_mul_f32_e32 v227, v93, v227
	v_mul_f32_e32 v227, 0x3fb8aa3b, v227
	v_exp_f32_e32 v226, v227
	s_waitcnt lgkmcnt(10)
	v_mfma_f32_16x16x32_f16 v[8:11], v[12:15], v[0:3], 0
	v_mfma_f32_16x16x32_f16 v[8:11], v[16:19], v[4:7], v[8:11]
	s_nop 7
	v_cndmask_b32_e64 v222, v8, v11, s[40:41]
	v_cndmask_b32_e64 v223, v9, v10, s[40:41]
	v_cndmask_b32_e64 v224, v10, v9, s[40:41]
	v_cndmask_b32_e64 v225, v11, v8, s[40:41]
	v_mul_f32_e32 v222, v222, v226
	v_mul_f32_e32 v223, v223, v226
	v_mul_f32_e32 v224, v224, v226
	v_mul_f32_e32 v225, v225, v226
	v_mul_f32_e32 v222, v80, v222
	v_mul_f32_e32 v223, v81, v223
	v_mul_f32_e32 v224, v82, v224
	v_mul_f32_e32 v225, v84, v225
	v_mul_f32_e32 v31, v222, v222
	v_fmac_f32_e32 v31, v223, v223
	v_fmac_f32_e32 v31, v224, v224
	v_fmac_f32_e32 v31, v225, v225
	v_add_f32_e32 v28, v28, v31
	s_mov_b64 exec, s[38:39]
	ds_write2_b32 v78, v222, v223 offset1:2
	ds_write2_b32 v78, v224, v225 offset0:4 offset1:6
	s_mov_b64 exec, -1
	v_add_u32_e32 v78, v78, v79
	s_waitcnt vmcnt(4)
	ds_bpermute_b32 v12, v30, v228
	ds_bpermute_b32 v13, v30, v229
	ds_bpermute_b32 v14, v30, v230
	ds_bpermute_b32 v15, v30, v231
	ds_bpermute_b32 v16, v30, v232
	ds_bpermute_b32 v17, v30, v233
	ds_bpermute_b32 v18, v30, v234
	ds_bpermute_b32 v19, v30, v235
	global_load_dwordx4 v[228:231], v85, s[70:71]
	global_load_dwordx4 v[232:235], v85, s[70:71] offset:64
	v_add_u32_e32 v85, 0x4000, v85
	v_add_u32_e32 v227, 0x280, v29
	v_cvt_f32_i32_e32 v227, v227
	v_mul_f32_e32 v227, v93, v227
	v_mul_f32_e32 v227, 0x3fb8aa3b, v227
	v_exp_f32_e32 v226, v227
	s_waitcnt lgkmcnt(10)
	v_mfma_f32_16x16x32_f16 v[8:11], v[20:23], v[0:3], 0
	v_mfma_f32_16x16x32_f16 v[8:11], v[24:27], v[4:7], v[8:11]
	s_nop 7
	v_cndmask_b32_e64 v222, v8, v11, s[40:41]
	v_cndmask_b32_e64 v223, v9, v10, s[40:41]
	v_cndmask_b32_e64 v224, v10, v9, s[40:41]
	v_cndmask_b32_e64 v225, v11, v8, s[40:41]
	v_mul_f32_e32 v222, v222, v226
	v_mul_f32_e32 v223, v223, v226
	v_mul_f32_e32 v224, v224, v226
	v_mul_f32_e32 v225, v225, v226
	v_mul_f32_e32 v222, v80, v222
	v_mul_f32_e32 v223, v81, v223
	v_mul_f32_e32 v224, v82, v224
	v_mul_f32_e32 v225, v84, v225
	v_mul_f32_e32 v31, v222, v222
	v_fmac_f32_e32 v31, v223, v223
	v_fmac_f32_e32 v31, v224, v224
	v_fmac_f32_e32 v31, v225, v225
	v_add_f32_e32 v28, v28, v31
	s_mov_b64 exec, s[38:39]
	ds_write2_b32 v78, v222, v223 offset1:2
	ds_write2_b32 v78, v224, v225 offset0:4 offset1:6
	s_mov_b64 exec, -1
	v_add_u32_e32 v78, v78, v79
	s_waitcnt vmcnt(4)
	ds_bpermute_b32 v20, v30, v236
	ds_bpermute_b32 v21, v30, v237
	ds_bpermute_b32 v22, v30, v238
	ds_bpermute_b32 v23, v30, v239
	ds_bpermute_b32 v24, v30, v240
	ds_bpermute_b32 v25, v30, v241
	ds_bpermute_b32 v26, v30, v242
	ds_bpermute_b32 v27, v30, v243
	global_load_dwordx4 v[236:239], v85, s[70:71]
	global_load_dwordx4 v[240:243], v85, s[70:71] offset:64
	v_add_u32_e32 v85, 0x4000, v85
	v_add_u32_e32 v227, 0x300, v29
	v_cvt_f32_i32_e32 v227, v227
	v_mul_f32_e32 v227, v93, v227
	v_mul_f32_e32 v227, 0x3fb8aa3b, v227
	v_exp_f32_e32 v226, v227
	s_waitcnt lgkmcnt(10)
; __device__ __forceinline__ void phase_hyena(KP kp_, int hf){ asm volatile("" : "+s"(kp_)); const Params p=load_params(kp_);
;     ...
;       _Pragma("unroll 8") for (int i=0;i<64;++i){ int tl=wid+8*i;
;         const _Float16* ap=a3+(size_t)(tl*16+n)*64+kg*8;
;         f16x8 a0=*(const f16x8*)ap, a1=*(const f16x8*)(ap+32);
;         f32x4 dd={0.f,0.f,0.f,0.f};
;         dd=__builtin_amdgcn_mfma_f32_16x16x32_f16(a0,bw0,dd,0,0,0);
;         dd=__builtin_amdgcn_mfma_f32_16x16x32_f16(a1,bw1,dd,0,0,0);
;         if (n<4){ float d0=__expf(dsc*(float)(tl*16)); int lag0=tl*16+kg*4;
;           float v0=dd[0]*d0*pj0, v1=dd[1]*d0*pj1, v2=dd[2]*d0*pj2, v3=dd[3]*d0*pj3;
;           if (!side1){ Zf[2*(lag0)+order]=v0; Zf[2*(lag0+1)+order]=v1; Zf[2*(lag0+2)+order]=v2; Zf[2*(lag0+3)+order]=v3; ssl+=v0*v0+v1*v1+v2*v2+v3*v3; }
;           else { if (lag0>=1){ Zf[2*(16384-lag0)+order]=v0; ssl+=v0*v0; }
;             Zf[2*(16384-lag0-1)+order]=v1; Zf[2*(16384-lag0-2)+order]=v2; Zf[2*(16384-lag0-3)+order]=v3; ssl+=v1*v1+v2*v2+v3*v3; } }
;       }
	v_mfma_f32_16x16x32_f16 v[8:11], v[12:15], v[0:3], 0
	v_mfma_f32_16x16x32_f16 v[8:11], v[16:19], v[4:7], v[8:11]
	s_nop 7
	v_cndmask_b32_e64 v222, v8, v11, s[40:41]
	v_cndmask_b32_e64 v223, v9, v10, s[40:41]
	v_cndmask_b32_e64 v224, v10, v9, s[40:41]
	v_cndmask_b32_e64 v225, v11, v8, s[40:41]
	v_mul_f32_e32 v222, v222, v226
	v_mul_f32_e32 v223, v223, v226
	v_mul_f32_e32 v224, v224, v226
	v_mul_f32_e32 v225, v225, v226
	v_mul_f32_e32 v222, v80, v222
	v_mul_f32_e32 v223, v81, v223
	v_mul_f32_e32 v224, v82, v224
	v_mul_f32_e32 v225, v84, v225
	v_mul_f32_e32 v31, v222, v222
	v_fmac_f32_e32 v31, v223, v223
	v_fmac_f32_e32 v31, v224, v224
	v_fmac_f32_e32 v31, v225, v225
	v_add_f32_e32 v28, v28, v31
	s_mov_b64 exec, s[38:39]
	ds_write2_b32 v78, v222, v223 offset1:2
	ds_write2_b32 v78, v224, v225 offset0:4 offset1:6
	s_mov_b64 exec, -1
	v_add_u32_e32 v78, v78, v79
	s_waitcnt vmcnt(4)
	ds_bpermute_b32 v12, v30, v244
	ds_bpermute_b32 v13, v30, v245
	ds_bpermute_b32 v14, v30, v246
	ds_bpermute_b32 v15, v30, v247
	ds_bpermute_b32 v16, v30, v248
	ds_bpermute_b32 v17, v30, v249
	ds_bpermute_b32 v18, v30, v250
	ds_bpermute_b32 v19, v30, v251
	global_load_dwordx4 v[244:247], v85, s[70:71]
	global_load_dwordx4 v[248:251], v85, s[70:71] offset:64
	v_add_u32_e32 v85, 0x4000, v85
	v_add_u32_e32 v227, 0x380, v29
	v_cvt_f32_i32_e32 v227, v227
	v_mul_f32_e32 v227, v93, v227
	v_mul_f32_e32 v227, 0x3fb8aa3b, v227
	v_exp_f32_e32 v226, v227
	s_waitcnt lgkmcnt(10)
	v_mfma_f32_16x16x32_f16 v[8:11], v[20:23], v[0:3], 0
	v_mfma_f32_16x16x32_f16 v[8:11], v[24:27], v[4:7], v[8:11]
	s_nop 7
	v_cndmask_b32_e64 v222, v8, v11, s[40:41]
	v_cndmask_b32_e64 v223, v9, v10, s[40:41]
	v_cndmask_b32_e64 v224, v10, v9, s[40:41]
	v_cndmask_b32_e64 v225, v11, v8, s[40:41]
	v_mul_f32_e32 v222, v222, v226
	v_mul_f32_e32 v223, v223, v226
	v_mul_f32_e32 v224, v224, v226
	v_mul_f32_e32 v225, v225, v226
	v_mul_f32_e32 v222, v80, v222
	v_mul_f32_e32 v223, v81, v223
	v_mul_f32_e32 v224, v82, v224
	v_mul_f32_e32 v225, v84, v225
	v_mul_f32_e32 v31, v222, v222
	v_fmac_f32_e32 v31, v223, v223
	v_fmac_f32_e32 v31, v224, v224
	v_fmac_f32_e32 v31, v225, v225
	v_add_f32_e32 v28, v28, v31
	s_mov_b64 exec, s[38:39]
	ds_write2_b32 v78, v222, v223 offset1:2
	ds_write2_b32 v78, v224, v225 offset0:4 offset1:6
	s_mov_b64 exec, -1
	v_add_u32_e32 v78, v78, v79
	s_waitcnt vmcnt(4)
	ds_bpermute_b32 v20, v30, v228
	ds_bpermute_b32 v21, v30, v229
	ds_bpermute_b32 v22, v30, v230
	ds_bpermute_b32 v23, v30, v231
	ds_bpermute_b32 v24, v30, v232
	ds_bpermute_b32 v25, v30, v233
	ds_bpermute_b32 v26, v30, v234
	ds_bpermute_b32 v27, v30, v235
	global_load_dwordx4 v[228:231], v85, s[70:71]
	global_load_dwordx4 v[232:235], v85, s[70:71] offset:64
	v_add_u32_e32 v85, 0x4000, v85
	v_add_u32_e32 v227, 0x400, v29
	v_cvt_f32_i32_e32 v227, v227
	v_mul_f32_e32 v227, v93, v227
	v_mul_f32_e32 v227, 0x3fb8aa3b, v227
	v_exp_f32_e32 v226, v227
	s_waitcnt lgkmcnt(10)
	v_mfma_f32_16x16x32_f16 v[8:11], v[12:15], v[0:3], 0
	v_mfma_f32_16x16x32_f16 v[8:11], v[16:19], v[4:7], v[8:11]
	s_nop 7
	v_cndmask_b32_e64 v222, v8, v11, s[40:41]
	v_cndmask_b32_e64 v223, v9, v10, s[40:41]
	v_cndmask_b32_e64 v224, v10, v9, s[40:41]
	v_cndmask_b32_e64 v225, v11, v8, s[40:41]
	v_mul_f32_e32 v222, v222, v226
	v_mul_f32_e32 v223, v223, v226
	v_mul_f32_e32 v224, v224, v226
	v_mul_f32_e32 v225, v225, v226
	v_mul_f32_e32 v222, v80, v222
	v_mul_f32_e32 v223, v81, v223
	v_mul_f32_e32 v224, v82, v224
	v_mul_f32_e32 v225, v84, v225
	v_mul_f32_e32 v31, v222, v222
	v_fmac_f32_e32 v31, v223, v223
	v_fmac_f32_e32 v31, v224, v224
	v_fmac_f32_e32 v31, v225, v225
	v_add_f32_e32 v28, v28, v31
	s_mov_b64 exec, s[38:39]
	ds_write2_b32 v78, v222, v223 offset1:2
	ds_write2_b32 v78, v224, v225 offset0:4 offset1:6
	s_mov_b64 exec, -1
	v_add_u32_e32 v78, v78, v79
	s_waitcnt vmcnt(4)
	ds_bpermute_b32 v12, v30, v236
	ds_bpermute_b32 v13, v30, v237
	ds_bpermute_b32 v14, v30, v238
	ds_bpermute_b32 v15, v30, v239
	ds_bpermute_b32 v16, v30, v240
	ds_bpermute_b32 v17, v30, v241
	ds_bpermute_b32 v18, v30, v242
	ds_bpermute_b32 v19, v30, v243
	global_load_dwordx4 v[236:239], v85, s[70:71]
	global_load_dwordx4 v[240:243], v85, s[70:71] offset:64
	v_add_u32_e32 v85, 0x4000, v85
	v_add_u32_e32 v227, 0x480, v29
	v_cvt_f32_i32_e32 v227, v227
	v_mul_f32_e32 v227, v93, v227
	v_mul_f32_e32 v227, 0x3fb8aa3b, v227
	v_exp_f32_e32 v226, v227
	s_waitcnt lgkmcnt(10)
	v_mfma_f32_16x16x32_f16 v[8:11], v[20:23], v[0:3], 0
	v_mfma_f32_16x16x32_f16 v[8:11], v[24:27], v[4:7], v[8:11]
	s_nop 7
	v_cndmask_b32_e64 v222, v8, v11, s[40:41]
	v_cndmask_b32_e64 v223, v9, v10, s[40:41]
	v_cndmask_b32_e64 v224, v10, v9, s[40:41]
	v_cndmask_b32_e64 v225, v11, v8, s[40:41]
	v_mul_f32_e32 v222, v222, v226
	v_mul_f32_e32 v223, v223, v226
	v_mul_f32_e32 v224, v224, v226
	v_mul_f32_e32 v225, v225, v226
	v_mul_f32_e32 v222, v80, v222
	v_mul_f32_e32 v223, v81, v223
	v_mul_f32_e32 v224, v82, v224
	v_mul_f32_e32 v225, v84, v225
	v_mul_f32_e32 v31, v222, v222
	v_fmac_f32_e32 v31, v223, v223
	v_fmac_f32_e32 v31, v224, v224
	v_fmac_f32_e32 v31, v225, v225
	v_add_f32_e32 v28, v28, v31
	s_mov_b64 exec, s[38:39]
	ds_write2_b32 v78, v222, v223 offset1:2
	ds_write2_b32 v78, v224, v225 offset0:4 offset1:6
	s_mov_b64 exec, -1
	v_add_u32_e32 v78, v78, v79
	s_waitcnt vmcnt(4)
	ds_bpermute_b32 v20, v30, v244
	ds_bpermute_b32 v21, v30, v245
	ds_bpermute_b32 v22, v30, v246
	ds_bpermute_b32 v23, v30, v247
	ds_bpermute_b32 v24, v30, v248
	ds_bpermute_b32 v25, v30, v249
	ds_bpermute_b32 v26, v30, v250
	ds_bpermute_b32 v27, v30, v251
	global_load_dwordx4 v[244:247], v85, s[70:71]
	global_load_dwordx4 v[248:251], v85, s[70:71] offset:64
	v_add_u32_e32 v85, 0x4000, v85
	v_add_u32_e32 v227, 0x500, v29
	v_cvt_f32_i32_e32 v227, v227
	v_mul_f32_e32 v227, v93, v227
	v_mul_f32_e32 v227, 0x3fb8aa3b, v227
	v_exp_f32_e32 v226, v227
	s_waitcnt lgkmcnt(10)
; __device__ __forceinline__ void phase_hyena(KP kp_, int hf){ asm volatile("" : "+s"(kp_)); const Params p=load_params(kp_);
;     ...
;       _Pragma("unroll 8") for (int i=0;i<64;++i){ int tl=wid+8*i;
;         const _Float16* ap=a3+(size_t)(tl*16+n)*64+kg*8;
;         f16x8 a0=*(const f16x8*)ap, a1=*(const f16x8*)(ap+32);
;         f32x4 dd={0.f,0.f,0.f,0.f};
;         dd=__builtin_amdgcn_mfma_f32_16x16x32_f16(a0,bw0,dd,0,0,0);
;         dd=__builtin_amdgcn_mfma_f32_16x16x32_f16(a1,bw1,dd,0,0,0);
;         if (n<4){ float d0=__expf(dsc*(float)(tl*16)); int lag0=tl*16+kg*4;
;           float v0=dd[0]*d0*pj0, v1=dd[1]*d0*pj1, v2=dd[2]*d0*pj2, v3=dd[3]*d0*pj3;
;           if (!side1){ Zf[2*(lag0)+order]=v0; Zf[2*(lag0+1)+order]=v1; Zf[2*(lag0+2)+order]=v2; Zf[2*(lag0+3)+order]=v3; ssl+=v0*v0+v1*v1+v2*v2+v3*v3; }
;           else { if (lag0>=1){ Zf[2*(16384-lag0)+order]=v0; ssl+=v0*v0; }
;             Zf[2*(16384-lag0-1)+order]=v1; Zf[2*(16384-lag0-2)+order]=v2; Zf[2*(16384-lag0-3)+order]=v3; ssl+=v1*v1+v2*v2+v3*v3; } }
;       }
	v_mfma_f32_16x16x32_f16 v[8:11], v[12:15], v[0:3], 0
	v_mfma_f32_16x16x32_f16 v[8:11], v[16:19], v[4:7], v[8:11]
	s_nop 7
	v_cndmask_b32_e64 v222, v8, v11, s[40:41]
	v_cndmask_b32_e64 v223, v9, v10, s[40:41]
	v_cndmask_b32_e64 v224, v10, v9, s[40:41]
	v_cndmask_b32_e64 v225, v11, v8, s[40:41]
	v_mul_f32_e32 v222, v222, v226
	v_mul_f32_e32 v223, v223, v226
	v_mul_f32_e32 v224, v224, v226
	v_mul_f32_e32 v225, v225, v226
	v_mul_f32_e32 v222, v80, v222
	v_mul_f32_e32 v223, v81, v223
	v_mul_f32_e32 v224, v82, v224
	v_mul_f32_e32 v225, v84, v225
	v_mul_f32_e32 v31, v222, v222
	v_fmac_f32_e32 v31, v223, v223
	v_fmac_f32_e32 v31, v224, v224
	v_fmac_f32_e32 v31, v225, v225
	v_add_f32_e32 v28, v28, v31
	s_mov_b64 exec, s[38:39]
	ds_write2_b32 v78, v222, v223 offset1:2
	ds_write2_b32 v78, v224, v225 offset0:4 offset1:6
	s_mov_b64 exec, -1
	v_add_u32_e32 v78, v78, v79
	s_waitcnt vmcnt(4)
	ds_bpermute_b32 v12, v30, v228
	ds_bpermute_b32 v13, v30, v229
	ds_bpermute_b32 v14, v30, v230
	ds_bpermute_b32 v15, v30, v231
	ds_bpermute_b32 v16, v30, v232
	ds_bpermute_b32 v17, v30, v233
	ds_bpermute_b32 v18, v30, v234
	ds_bpermute_b32 v19, v30, v235
	global_load_dwordx4 v[228:231], v85, s[70:71]
	global_load_dwordx4 v[232:235], v85, s[70:71] offset:64
	v_add_u32_e32 v85, 0x4000, v85
	v_add_u32_e32 v227, 0x580, v29
	v_cvt_f32_i32_e32 v227, v227
	v_mul_f32_e32 v227, v93, v227
	v_mul_f32_e32 v227, 0x3fb8aa3b, v227
	v_exp_f32_e32 v226, v227
	s_waitcnt lgkmcnt(10)
	v_mfma_f32_16x16x32_f16 v[8:11], v[20:23], v[0:3], 0
	v_mfma_f32_16x16x32_f16 v[8:11], v[24:27], v[4:7], v[8:11]
	s_nop 7
	v_cndmask_b32_e64 v222, v8, v11, s[40:41]
	v_cndmask_b32_e64 v223, v9, v10, s[40:41]
	v_cndmask_b32_e64 v224, v10, v9, s[40:41]
	v_cndmask_b32_e64 v225, v11, v8, s[40:41]
	v_mul_f32_e32 v222, v222, v226
	v_mul_f32_e32 v223, v223, v226
	v_mul_f32_e32 v224, v224, v226
	v_mul_f32_e32 v225, v225, v226
	v_mul_f32_e32 v222, v80, v222
	v_mul_f32_e32 v223, v81, v223
	v_mul_f32_e32 v224, v82, v224
	v_mul_f32_e32 v225, v84, v225
	v_mul_f32_e32 v31, v222, v222
	v_fmac_f32_e32 v31, v223, v223
	v_fmac_f32_e32 v31, v224, v224
	v_fmac_f32_e32 v31, v225, v225
	v_add_f32_e32 v28, v28, v31
	s_mov_b64 exec, s[38:39]
	ds_write2_b32 v78, v222, v223 offset1:2
	ds_write2_b32 v78, v224, v225 offset0:4 offset1:6
	s_mov_b64 exec, -1
	v_add_u32_e32 v78, v78, v79
	s_waitcnt vmcnt(4)
	ds_bpermute_b32 v20, v30, v236
	ds_bpermute_b32 v21, v30, v237
	ds_bpermute_b32 v22, v30, v238
	ds_bpermute_b32 v23, v30, v239
	ds_bpermute_b32 v24, v30, v240
	ds_bpermute_b32 v25, v30, v241
	ds_bpermute_b32 v26, v30, v242
	ds_bpermute_b32 v27, v30, v243
	global_load_dwordx4 v[236:239], v85, s[70:71]
	global_load_dwordx4 v[240:243], v85, s[70:71] offset:64
	v_add_u32_e32 v85, 0x4000, v85
	v_add_u32_e32 v227, 0x600, v29
	v_cvt_f32_i32_e32 v227, v227
	v_mul_f32_e32 v227, v93, v227
	v_mul_f32_e32 v227, 0x3fb8aa3b, v227
	v_exp_f32_e32 v226, v227
	s_waitcnt lgkmcnt(10)
	v_mfma_f32_16x16x32_f16 v[8:11], v[12:15], v[0:3], 0
	v_mfma_f32_16x16x32_f16 v[8:11], v[16:19], v[4:7], v[8:11]
	s_nop 7
	v_cndmask_b32_e64 v222, v8, v11, s[40:41]
	v_cndmask_b32_e64 v223, v9, v10, s[40:41]
	v_cndmask_b32_e64 v224, v10, v9, s[40:41]
	v_cndmask_b32_e64 v225, v11, v8, s[40:41]
	v_mul_f32_e32 v222, v222, v226
	v_mul_f32_e32 v223, v223, v226
	v_mul_f32_e32 v224, v224, v226
	v_mul_f32_e32 v225, v225, v226
	v_mul_f32_e32 v222, v80, v222
	v_mul_f32_e32 v223, v81, v223
	v_mul_f32_e32 v224, v82, v224
	v_mul_f32_e32 v225, v84, v225
	v_mul_f32_e32 v31, v222, v222
	v_fmac_f32_e32 v31, v223, v223
	v_fmac_f32_e32 v31, v224, v224
	v_fmac_f32_e32 v31, v225, v225
	v_add_f32_e32 v28, v28, v31
	s_mov_b64 exec, s[38:39]
	ds_write2_b32 v78, v222, v223 offset1:2
	ds_write2_b32 v78, v224, v225 offset0:4 offset1:6
	s_mov_b64 exec, -1
	v_add_u32_e32 v78, v78, v79
	s_waitcnt vmcnt(4)
	ds_bpermute_b32 v12, v30, v244
	ds_bpermute_b32 v13, v30, v245
	ds_bpermute_b32 v14, v30, v246
	ds_bpermute_b32 v15, v30, v247
	ds_bpermute_b32 v16, v30, v248
	ds_bpermute_b32 v17, v30, v249
	ds_bpermute_b32 v18, v30, v250
	ds_bpermute_b32 v19, v30, v251
	global_load_dwordx4 v[244:247], v85, s[70:71]
	global_load_dwordx4 v[248:251], v85, s[70:71] offset:64
	v_add_u32_e32 v85, 0x4000, v85
	v_add_u32_e32 v227, 0x680, v29
	v_cvt_f32_i32_e32 v227, v227
	v_mul_f32_e32 v227, v93, v227
	v_mul_f32_e32 v227, 0x3fb8aa3b, v227
	v_exp_f32_e32 v226, v227
	s_waitcnt lgkmcnt(10)
	v_mfma_f32_16x16x32_f16 v[8:11], v[20:23], v[0:3], 0
	v_mfma_f32_16x16x32_f16 v[8:11], v[24:27], v[4:7], v[8:11]
	s_nop 7
	v_cndmask_b32_e64 v222, v8, v11, s[40:41]
	v_cndmask_b32_e64 v223, v9, v10, s[40:41]
	v_cndmask_b32_e64 v224, v10, v9, s[40:41]
	v_cndmask_b32_e64 v225, v11, v8, s[40:41]
	v_mul_f32_e32 v222, v222, v226
	v_mul_f32_e32 v223, v223, v226
	v_mul_f32_e32 v224, v224, v226
	v_mul_f32_e32 v225, v225, v226
	v_mul_f32_e32 v222, v80, v222
	v_mul_f32_e32 v223, v81, v223
	v_mul_f32_e32 v224, v82, v224
	v_mul_f32_e32 v225, v84, v225
	v_mul_f32_e32 v31, v222, v222
	v_fmac_f32_e32 v31, v223, v223
	v_fmac_f32_e32 v31, v224, v224
	v_fmac_f32_e32 v31, v225, v225
	v_add_f32_e32 v28, v28, v31
	s_mov_b64 exec, s[38:39]
	ds_write2_b32 v78, v222, v223 offset1:2
	ds_write2_b32 v78, v224, v225 offset0:4 offset1:6
	s_mov_b64 exec, -1
	v_add_u32_e32 v78, v78, v79
	s_waitcnt vmcnt(4)
	ds_bpermute_b32 v20, v30, v228
	ds_bpermute_b32 v21, v30, v229
	ds_bpermute_b32 v22, v30, v230
	ds_bpermute_b32 v23, v30, v231
	ds_bpermute_b32 v24, v30, v232
	ds_bpermute_b32 v25, v30, v233
	ds_bpermute_b32 v26, v30, v234
	ds_bpermute_b32 v27, v30, v235
	global_load_dwordx4 v[228:231], v85, s[70:71]
	global_load_dwordx4 v[232:235], v85, s[70:71] offset:64
	v_add_u32_e32 v85, 0x4000, v85
	v_add_u32_e32 v227, 0x700, v29
	v_cvt_f32_i32_e32 v227, v227
	v_mul_f32_e32 v227, v93, v227
	v_mul_f32_e32 v227, 0x3fb8aa3b, v227
	v_exp_f32_e32 v226, v227
	s_waitcnt lgkmcnt(10)
; __device__ __forceinline__ void phase_hyena(KP kp_, int hf){ asm volatile("" : "+s"(kp_)); const Params p=load_params(kp_);
;     ...
;       _Pragma("unroll 8") for (int i=0;i<64;++i){ int tl=wid+8*i;
;         const _Float16* ap=a3+(size_t)(tl*16+n)*64+kg*8;
;         f16x8 a0=*(const f16x8*)ap, a1=*(const f16x8*)(ap+32);
;         f32x4 dd={0.f,0.f,0.f,0.f};
;         dd=__builtin_amdgcn_mfma_f32_16x16x32_f16(a0,bw0,dd,0,0,0);
;         dd=__builtin_amdgcn_mfma_f32_16x16x32_f16(a1,bw1,dd,0,0,0);
;         if (n<4){ float d0=__expf(dsc*(float)(tl*16)); int lag0=tl*16+kg*4;
;           float v0=dd[0]*d0*pj0, v1=dd[1]*d0*pj1, v2=dd[2]*d0*pj2, v3=dd[3]*d0*pj3;
;           if (!side1){ Zf[2*(lag0)+order]=v0; Zf[2*(lag0+1)+order]=v1; Zf[2*(lag0+2)+order]=v2; Zf[2*(lag0+3)+order]=v3; ssl+=v0*v0+v1*v1+v2*v2+v3*v3; }
;           else { if (lag0>=1){ Zf[2*(16384-lag0)+order]=v0; ssl+=v0*v0; }
;             Zf[2*(16384-lag0-1)+order]=v1; Zf[2*(16384-lag0-2)+order]=v2; Zf[2*(16384-lag0-3)+order]=v3; ssl+=v1*v1+v2*v2+v3*v3; } }
;       }
	v_mfma_f32_16x16x32_f16 v[8:11], v[12:15], v[0:3], 0
	v_mfma_f32_16x16x32_f16 v[8:11], v[16:19], v[4:7], v[8:11]
	s_nop 7
	v_cndmask_b32_e64 v222, v8, v11, s[40:41]
	v_cndmask_b32_e64 v223, v9, v10, s[40:41]
	v_cndmask_b32_e64 v224, v10, v9, s[40:41]
	v_cndmask_b32_e64 v225, v11, v8, s[40:41]
	v_mul_f32_e32 v222, v222, v226
	v_mul_f32_e32 v223, v223, v226
	v_mul_f32_e32 v224, v224, v226
	v_mul_f32_e32 v225, v225, v226
	v_mul_f32_e32 v222, v80, v222
	v_mul_f32_e32 v223, v81, v223
	v_mul_f32_e32 v224, v82, v224
	v_mul_f32_e32 v225, v84, v225
	v_mul_f32_e32 v31, v222, v222
	v_fmac_f32_e32 v31, v223, v223
	v_fmac_f32_e32 v31, v224, v224
	v_fmac_f32_e32 v31, v225, v225
	v_add_f32_e32 v28, v28, v31
	s_mov_b64 exec, s[38:39]
	ds_write2_b32 v78, v222, v223 offset1:2
	ds_write2_b32 v78, v224, v225 offset0:4 offset1:6
	s_mov_b64 exec, -1
	v_add_u32_e32 v78, v78, v79
	s_waitcnt vmcnt(4)
	ds_bpermute_b32 v12, v30, v236
	ds_bpermute_b32 v13, v30, v237
	ds_bpermute_b32 v14, v30, v238
	ds_bpermute_b32 v15, v30, v239
	ds_bpermute_b32 v16, v30, v240
	ds_bpermute_b32 v17, v30, v241
	ds_bpermute_b32 v18, v30, v242
	ds_bpermute_b32 v19, v30, v243
	global_load_dwordx4 v[236:239], v85, s[70:71]
	global_load_dwordx4 v[240:243], v85, s[70:71] offset:64
	v_add_u32_e32 v85, 0x4000, v85
	v_add_u32_e32 v227, 0x780, v29
	v_cvt_f32_i32_e32 v227, v227
	v_mul_f32_e32 v227, v93, v227
	v_mul_f32_e32 v227, 0x3fb8aa3b, v227
	v_exp_f32_e32 v226, v227
	s_waitcnt lgkmcnt(10)
	v_mfma_f32_16x16x32_f16 v[8:11], v[20:23], v[0:3], 0
	v_mfma_f32_16x16x32_f16 v[8:11], v[24:27], v[4:7], v[8:11]
	s_nop 7
	v_cndmask_b32_e64 v222, v8, v11, s[40:41]
	v_cndmask_b32_e64 v223, v9, v10, s[40:41]
	v_cndmask_b32_e64 v224, v10, v9, s[40:41]
	v_cndmask_b32_e64 v225, v11, v8, s[40:41]
	v_mul_f32_e32 v222, v222, v226
	v_mul_f32_e32 v223, v223, v226
	v_mul_f32_e32 v224, v224, v226
	v_mul_f32_e32 v225, v225, v226
	v_mul_f32_e32 v222, v80, v222
	v_mul_f32_e32 v223, v81, v223
	v_mul_f32_e32 v224, v82, v224
	v_mul_f32_e32 v225, v84, v225
	v_mul_f32_e32 v31, v222, v222
	v_fmac_f32_e32 v31, v223, v223
	v_fmac_f32_e32 v31, v224, v224
	v_fmac_f32_e32 v31, v225, v225
	v_add_f32_e32 v28, v28, v31
	s_mov_b64 exec, s[38:39]
	ds_write2_b32 v78, v222, v223 offset1:2
	ds_write2_b32 v78, v224, v225 offset0:4 offset1:6
	s_mov_b64 exec, -1
	v_add_u32_e32 v78, v78, v79
	s_waitcnt vmcnt(4)
	ds_bpermute_b32 v20, v30, v244
	ds_bpermute_b32 v21, v30, v245
	ds_bpermute_b32 v22, v30, v246
	ds_bpermute_b32 v23, v30, v247
	ds_bpermute_b32 v24, v30, v248
	ds_bpermute_b32 v25, v30, v249
	ds_bpermute_b32 v26, v30, v250
	ds_bpermute_b32 v27, v30, v251
	global_load_dwordx4 v[244:247], v85, s[70:71]
	global_load_dwordx4 v[248:251], v85, s[70:71] offset:64
	v_add_u32_e32 v85, 0x4000, v85
	v_add_u32_e32 v227, 0x800, v29
	v_cvt_f32_i32_e32 v227, v227
	v_mul_f32_e32 v227, v93, v227
	v_mul_f32_e32 v227, 0x3fb8aa3b, v227
	v_exp_f32_e32 v226, v227
	s_waitcnt lgkmcnt(10)
	v_mfma_f32_16x16x32_f16 v[8:11], v[12:15], v[0:3], 0
	v_mfma_f32_16x16x32_f16 v[8:11], v[16:19], v[4:7], v[8:11]
	s_nop 7
	v_cndmask_b32_e64 v222, v8, v11, s[40:41]
	v_cndmask_b32_e64 v223, v9, v10, s[40:41]
	v_cndmask_b32_e64 v224, v10, v9, s[40:41]
	v_cndmask_b32_e64 v225, v11, v8, s[40:41]
	v_mul_f32_e32 v222, v222, v226
	v_mul_f32_e32 v223, v223, v226
	v_mul_f32_e32 v224, v224, v226
	v_mul_f32_e32 v225, v225, v226
	v_mul_f32_e32 v222, v80, v222
	v_mul_f32_e32 v223, v81, v223
	v_mul_f32_e32 v224, v82, v224
	v_mul_f32_e32 v225, v84, v225
	v_mul_f32_e32 v31, v222, v222
	v_fmac_f32_e32 v31, v223, v223
	v_fmac_f32_e32 v31, v224, v224
	v_fmac_f32_e32 v31, v225, v225
	v_add_f32_e32 v28, v28, v31
	s_mov_b64 exec, s[38:39]
	ds_write2_b32 v78, v222, v223 offset1:2
	ds_write2_b32 v78, v224, v225 offset0:4 offset1:6
	s_mov_b64 exec, -1
	v_add_u32_e32 v78, v78, v79
	s_waitcnt vmcnt(4)
	ds_bpermute_b32 v12, v30, v228
	ds_bpermute_b32 v13, v30, v229
	ds_bpermute_b32 v14, v30, v230
	ds_bpermute_b32 v15, v30, v231
	ds_bpermute_b32 v16, v30, v232
	ds_bpermute_b32 v17, v30, v233
	ds_bpermute_b32 v18, v30, v234
	ds_bpermute_b32 v19, v30, v235
	global_load_dwordx4 v[228:231], v85, s[70:71]
	global_load_dwordx4 v[232:235], v85, s[70:71] offset:64
	v_add_u32_e32 v85, 0x4000, v85
	v_add_u32_e32 v227, 0x880, v29
	v_cvt_f32_i32_e32 v227, v227
	v_mul_f32_e32 v227, v93, v227
	v_mul_f32_e32 v227, 0x3fb8aa3b, v227
	v_exp_f32_e32 v226, v227
	s_waitcnt lgkmcnt(10)
	v_mfma_f32_16x16x32_f16 v[8:11], v[20:23], v[0:3], 0
	v_mfma_f32_16x16x32_f16 v[8:11], v[24:27], v[4:7], v[8:11]
	s_nop 7
	v_cndmask_b32_e64 v222, v8, v11, s[40:41]
	v_cndmask_b32_e64 v223, v9, v10, s[40:41]
	v_cndmask_b32_e64 v224, v10, v9, s[40:41]
	v_cndmask_b32_e64 v225, v11, v8, s[40:41]
	v_mul_f32_e32 v222, v222, v226
	v_mul_f32_e32 v223, v223, v226
	v_mul_f32_e32 v224, v224, v226
	v_mul_f32_e32 v225, v225, v226
	v_mul_f32_e32 v222, v80, v222
	v_mul_f32_e32 v223, v81, v223
	v_mul_f32_e32 v224, v82, v224
	v_mul_f32_e32 v225, v84, v225
	v_mul_f32_e32 v31, v222, v222
	v_fmac_f32_e32 v31, v223, v223
	v_fmac_f32_e32 v31, v224, v224
	v_fmac_f32_e32 v31, v225, v225
	v_add_f32_e32 v28, v28, v31
	s_mov_b64 exec, s[38:39]
	ds_write2_b32 v78, v222, v223 offset1:2
	ds_write2_b32 v78, v224, v225 offset0:4 offset1:6
	s_mov_b64 exec, -1
	v_add_u32_e32 v78, v78, v79
	s_waitcnt vmcnt(4)
	ds_bpermute_b32 v20, v30, v236
	ds_bpermute_b32 v21, v30, v237
	ds_bpermute_b32 v22, v30, v238
	ds_bpermute_b32 v23, v30, v239
	ds_bpermute_b32 v24, v30, v240
	ds_bpermute_b32 v25, v30, v241
	ds_bpermute_b32 v26, v30, v242
	ds_bpermute_b32 v27, v30, v243
	global_load_dwordx4 v[236:239], v85, s[70:71]
	global_load_dwordx4 v[240:243], v85, s[70:71] offset:64
	v_add_u32_e32 v85, 0x4000, v85
	v_add_u32_e32 v227, 0x900, v29
	v_cvt_f32_i32_e32 v227, v227
	v_mul_f32_e32 v227, v93, v227
	v_mul_f32_e32 v227, 0x3fb8aa3b, v227
	v_exp_f32_e32 v226, v227
	s_waitcnt lgkmcnt(10)
; __device__ __forceinline__ void phase_hyena(KP kp_, int hf){ asm volatile("" : "+s"(kp_)); const Params p=load_params(kp_);
;     ...
;       _Pragma("unroll 8") for (int i=0;i<64;++i){ int tl=wid+8*i;
;         const _Float16* ap=a3+(size_t)(tl*16+n)*64+kg*8;
;         f16x8 a0=*(const f16x8*)ap, a1=*(const f16x8*)(ap+32);
;         f32x4 dd={0.f,0.f,0.f,0.f};
;         dd=__builtin_amdgcn_mfma_f32_16x16x32_f16(a0,bw0,dd,0,0,0);
;         dd=__builtin_amdgcn_mfma_f32_16x16x32_f16(a1,bw1,dd,0,0,0);
;         if (n<4){ float d0=__expf(dsc*(float)(tl*16)); int lag0=tl*16+kg*4;
;           float v0=dd[0]*d0*pj0, v1=dd[1]*d0*pj1, v2=dd[2]*d0*pj2, v3=dd[3]*d0*pj3;
;           if (!side1){ Zf[2*(lag0)+order]=v0; Zf[2*(lag0+1)+order]=v1; Zf[2*(lag0+2)+order]=v2; Zf[2*(lag0+3)+order]=v3; ssl+=v0*v0+v1*v1+v2*v2+v3*v3; }
;           else { if (lag0>=1){ Zf[2*(16384-lag0)+order]=v0; ssl+=v0*v0; }
;             Zf[2*(16384-lag0-1)+order]=v1; Zf[2*(16384-lag0-2)+order]=v2; Zf[2*(16384-lag0-3)+order]=v3; ssl+=v1*v1+v2*v2+v3*v3; } }
;       }
	v_mfma_f32_16x16x32_f16 v[8:11], v[12:15], v[0:3], 0
	v_mfma_f32_16x16x32_f16 v[8:11], v[16:19], v[4:7], v[8:11]
	s_nop 7
	v_cndmask_b32_e64 v222, v8, v11, s[40:41]
	v_cndmask_b32_e64 v223, v9, v10, s[40:41]
	v_cndmask_b32_e64 v224, v10, v9, s[40:41]
	v_cndmask_b32_e64 v225, v11, v8, s[40:41]
	v_mul_f32_e32 v222, v222, v226
	v_mul_f32_e32 v223, v223, v226
	v_mul_f32_e32 v224, v224, v226
	v_mul_f32_e32 v225, v225, v226
	v_mul_f32_e32 v222, v80, v222
	v_mul_f32_e32 v223, v81, v223
	v_mul_f32_e32 v224, v82, v224
	v_mul_f32_e32 v225, v84, v225
	v_mul_f32_e32 v31, v222, v222
	v_fmac_f32_e32 v31, v223, v223
	v_fmac_f32_e32 v31, v224, v224
	v_fmac_f32_e32 v31, v225, v225
	v_add_f32_e32 v28, v28, v31
	s_mov_b64 exec, s[38:39]
	ds_write2_b32 v78, v222, v223 offset1:2
	ds_write2_b32 v78, v224, v225 offset0:4 offset1:6
	s_mov_b64 exec, -1
	v_add_u32_e32 v78, v78, v79
	s_waitcnt vmcnt(4)
	ds_bpermute_b32 v12, v30, v244
	ds_bpermute_b32 v13, v30, v245
	ds_bpermute_b32 v14, v30, v246
	ds_bpermute_b32 v15, v30, v247
	ds_bpermute_b32 v16, v30, v248
	ds_bpermute_b32 v17, v30, v249
	ds_bpermute_b32 v18, v30, v250
	ds_bpermute_b32 v19, v30, v251
	global_load_dwordx4 v[244:247], v85, s[70:71]
	global_load_dwordx4 v[248:251], v85, s[70:71] offset:64
	v_add_u32_e32 v85, 0x4000, v85
	v_add_u32_e32 v227, 0x980, v29
	v_cvt_f32_i32_e32 v227, v227
	v_mul_f32_e32 v227, v93, v227
	v_mul_f32_e32 v227, 0x3fb8aa3b, v227
	v_exp_f32_e32 v226, v227
	s_waitcnt lgkmcnt(10)
	v_mfma_f32_16x16x32_f16 v[8:11], v[20:23], v[0:3], 0
	v_mfma_f32_16x16x32_f16 v[8:11], v[24:27], v[4:7], v[8:11]
	s_nop 7
	v_cndmask_b32_e64 v222, v8, v11, s[40:41]
	v_cndmask_b32_e64 v223, v9, v10, s[40:41]
	v_cndmask_b32_e64 v224, v10, v9, s[40:41]
	v_cndmask_b32_e64 v225, v11, v8, s[40:41]
	v_mul_f32_e32 v222, v222, v226
	v_mul_f32_e32 v223, v223, v226
	v_mul_f32_e32 v224, v224, v226
	v_mul_f32_e32 v225, v225, v226
	v_mul_f32_e32 v222, v80, v222
	v_mul_f32_e32 v223, v81, v223
	v_mul_f32_e32 v224, v82, v224
	v_mul_f32_e32 v225, v84, v225
	v_mul_f32_e32 v31, v222, v222
	v_fmac_f32_e32 v31, v223, v223
	v_fmac_f32_e32 v31, v224, v224
	v_fmac_f32_e32 v31, v225, v225
	v_add_f32_e32 v28, v28, v31
	s_mov_b64 exec, s[38:39]
	ds_write2_b32 v78, v222, v223 offset1:2
	ds_write2_b32 v78, v224, v225 offset0:4 offset1:6
	s_mov_b64 exec, -1
	v_add_u32_e32 v78, v78, v79
	s_waitcnt vmcnt(4)
	ds_bpermute_b32 v20, v30, v228
	ds_bpermute_b32 v21, v30, v229
	ds_bpermute_b32 v22, v30, v230
	ds_bpermute_b32 v23, v30, v231
	ds_bpermute_b32 v24, v30, v232
	ds_bpermute_b32 v25, v30, v233
	ds_bpermute_b32 v26, v30, v234
	ds_bpermute_b32 v27, v30, v235
	global_load_dwordx4 v[228:231], v85, s[70:71]
	global_load_dwordx4 v[232:235], v85, s[70:71] offset:64
	v_add_u32_e32 v85, 0x4000, v85
	v_add_u32_e32 v227, 0xa00, v29
	v_cvt_f32_i32_e32 v227, v227
	v_mul_f32_e32 v227, v93, v227
	v_mul_f32_e32 v227, 0x3fb8aa3b, v227
	v_exp_f32_e32 v226, v227
	s_waitcnt lgkmcnt(10)
	v_mfma_f32_16x16x32_f16 v[8:11], v[12:15], v[0:3], 0
	v_mfma_f32_16x16x32_f16 v[8:11], v[16:19], v[4:7], v[8:11]
	s_nop 7
	v_cndmask_b32_e64 v222, v8, v11, s[40:41]
	v_cndmask_b32_e64 v223, v9, v10, s[40:41]
	v_cndmask_b32_e64 v224, v10, v9, s[40:41]
	v_cndmask_b32_e64 v225, v11, v8, s[40:41]
	v_mul_f32_e32 v222, v222, v226
	v_mul_f32_e32 v223, v223, v226
	v_mul_f32_e32 v224, v224, v226
	v_mul_f32_e32 v225, v225, v226
	v_mul_f32_e32 v222, v80, v222
	v_mul_f32_e32 v223, v81, v223
	v_mul_f32_e32 v224, v82, v224
	v_mul_f32_e32 v225, v84, v225
	v_mul_f32_e32 v31, v222, v222
	v_fmac_f32_e32 v31, v223, v223
	v_fmac_f32_e32 v31, v224, v224
	v_fmac_f32_e32 v31, v225, v225
	v_add_f32_e32 v28, v28, v31
	s_mov_b64 exec, s[38:39]
	ds_write2_b32 v78, v222, v223 offset1:2
	ds_write2_b32 v78, v224, v225 offset0:4 offset1:6
	s_mov_b64 exec, -1
	v_add_u32_e32 v78, v78, v79
	s_waitcnt vmcnt(4)
	ds_bpermute_b32 v12, v30, v236
	ds_bpermute_b32 v13, v30, v237
	ds_bpermute_b32 v14, v30, v238
	ds_bpermute_b32 v15, v30, v239
	ds_bpermute_b32 v16, v30, v240
	ds_bpermute_b32 v17, v30, v241
	ds_bpermute_b32 v18, v30, v242
	ds_bpermute_b32 v19, v30, v243
	global_load_dwordx4 v[236:239], v85, s[70:71]
	global_load_dwordx4 v[240:243], v85, s[70:71] offset:64
	v_add_u32_e32 v85, 0x4000, v85
	v_add_u32_e32 v227, 0xa80, v29
	v_cvt_f32_i32_e32 v227, v227
	v_mul_f32_e32 v227, v93, v227
	v_mul_f32_e32 v227, 0x3fb8aa3b, v227
	v_exp_f32_e32 v226, v227
	s_waitcnt lgkmcnt(10)
	v_mfma_f32_16x16x32_f16 v[8:11], v[20:23], v[0:3], 0
	v_mfma_f32_16x16x32_f16 v[8:11], v[24:27], v[4:7], v[8:11]
	s_nop 7
	v_cndmask_b32_e64 v222, v8, v11, s[40:41]
	v_cndmask_b32_e64 v223, v9, v10, s[40:41]
	v_cndmask_b32_e64 v224, v10, v9, s[40:41]
	v_cndmask_b32_e64 v225, v11, v8, s[40:41]
	v_mul_f32_e32 v222, v222, v226
	v_mul_f32_e32 v223, v223, v226
	v_mul_f32_e32 v224, v224, v226
	v_mul_f32_e32 v225, v225, v226
	v_mul_f32_e32 v222, v80, v222
	v_mul_f32_e32 v223, v81, v223
	v_mul_f32_e32 v224, v82, v224
	v_mul_f32_e32 v225, v84, v225
	v_mul_f32_e32 v31, v222, v222
	v_fmac_f32_e32 v31, v223, v223
	v_fmac_f32_e32 v31, v224, v224
	v_fmac_f32_e32 v31, v225, v225
	v_add_f32_e32 v28, v28, v31
	s_mov_b64 exec, s[38:39]
	ds_write2_b32 v78, v222, v223 offset1:2
	ds_write2_b32 v78, v224, v225 offset0:4 offset1:6
	s_mov_b64 exec, -1
	v_add_u32_e32 v78, v78, v79
	s_waitcnt vmcnt(4)
	ds_bpermute_b32 v20, v30, v244
	ds_bpermute_b32 v21, v30, v245
	ds_bpermute_b32 v22, v30, v246
	ds_bpermute_b32 v23, v30, v247
	ds_bpermute_b32 v24, v30, v248
	ds_bpermute_b32 v25, v30, v249
	ds_bpermute_b32 v26, v30, v250
	ds_bpermute_b32 v27, v30, v251
	global_load_dwordx4 v[244:247], v85, s[70:71]
	global_load_dwordx4 v[248:251], v85, s[70:71] offset:64
	v_add_u32_e32 v85, 0x4000, v85
	v_add_u32_e32 v227, 0xb00, v29
	v_cvt_f32_i32_e32 v227, v227
	v_mul_f32_e32 v227, v93, v227
	v_mul_f32_e32 v227, 0x3fb8aa3b, v227
	v_exp_f32_e32 v226, v227
	s_waitcnt lgkmcnt(10)
; __device__ __forceinline__ void phase_hyena(KP kp_, int hf){ asm volatile("" : "+s"(kp_)); const Params p=load_params(kp_);
;     ...
;       _Pragma("unroll 8") for (int i=0;i<64;++i){ int tl=wid+8*i;
;         const _Float16* ap=a3+(size_t)(tl*16+n)*64+kg*8;
;         f16x8 a0=*(const f16x8*)ap, a1=*(const f16x8*)(ap+32);
;         f32x4 dd={0.f,0.f,0.f,0.f};
;         dd=__builtin_amdgcn_mfma_f32_16x16x32_f16(a0,bw0,dd,0,0,0);
;         dd=__builtin_amdgcn_mfma_f32_16x16x32_f16(a1,bw1,dd,0,0,0);
;         if (n<4){ float d0=__expf(dsc*(float)(tl*16)); int lag0=tl*16+kg*4;
;           float v0=dd[0]*d0*pj0, v1=dd[1]*d0*pj1, v2=dd[2]*d0*pj2, v3=dd[3]*d0*pj3;
;           if (!side1){ Zf[2*(lag0)+order]=v0; Zf[2*(lag0+1)+order]=v1; Zf[2*(lag0+2)+order]=v2; Zf[2*(lag0+3)+order]=v3; ssl+=v0*v0+v1*v1+v2*v2+v3*v3; }
;           else { if (lag0>=1){ Zf[2*(16384-lag0)+order]=v0; ssl+=v0*v0; }
;             Zf[2*(16384-lag0-1)+order]=v1; Zf[2*(16384-lag0-2)+order]=v2; Zf[2*(16384-lag0-3)+order]=v3; ssl+=v1*v1+v2*v2+v3*v3; } }
;       }
	v_mfma_f32_16x16x32_f16 v[8:11], v[12:15], v[0:3], 0
	v_mfma_f32_16x16x32_f16 v[8:11], v[16:19], v[4:7], v[8:11]
	s_nop 7
	v_cndmask_b32_e64 v222, v8, v11, s[40:41]
	v_cndmask_b32_e64 v223, v9, v10, s[40:41]
	v_cndmask_b32_e64 v224, v10, v9, s[40:41]
	v_cndmask_b32_e64 v225, v11, v8, s[40:41]
	v_mul_f32_e32 v222, v222, v226
	v_mul_f32_e32 v223, v223, v226
	v_mul_f32_e32 v224, v224, v226
	v_mul_f32_e32 v225, v225, v226
	v_mul_f32_e32 v222, v80, v222
	v_mul_f32_e32 v223, v81, v223
	v_mul_f32_e32 v224, v82, v224
	v_mul_f32_e32 v225, v84, v225
	v_mul_f32_e32 v31, v222, v222
	v_fmac_f32_e32 v31, v223, v223
	v_fmac_f32_e32 v31, v224, v224
	v_fmac_f32_e32 v31, v225, v225
	v_add_f32_e32 v28, v28, v31
	s_mov_b64 exec, s[38:39]
	ds_write2_b32 v78, v222, v223 offset1:2
	ds_write2_b32 v78, v224, v225 offset0:4 offset1:6
	s_mov_b64 exec, -1
	v_add_u32_e32 v78, v78, v79
	s_waitcnt vmcnt(4)
	ds_bpermute_b32 v12, v30, v228
	ds_bpermute_b32 v13, v30, v229
	ds_bpermute_b32 v14, v30, v230
	ds_bpermute_b32 v15, v30, v231
	ds_bpermute_b32 v16, v30, v232
	ds_bpermute_b32 v17, v30, v233
	ds_bpermute_b32 v18, v30, v234
	ds_bpermute_b32 v19, v30, v235
	global_load_dwordx4 v[228:231], v85, s[70:71]
	global_load_dwordx4 v[232:235], v85, s[70:71] offset:64
	v_add_u32_e32 v85, 0x4000, v85
	v_add_u32_e32 v227, 0xb80, v29
	v_cvt_f32_i32_e32 v227, v227
	v_mul_f32_e32 v227, v93, v227
	v_mul_f32_e32 v227, 0x3fb8aa3b, v227
	v_exp_f32_e32 v226, v227
	s_waitcnt lgkmcnt(10)
	v_mfma_f32_16x16x32_f16 v[8:11], v[20:23], v[0:3], 0
	v_mfma_f32_16x16x32_f16 v[8:11], v[24:27], v[4:7], v[8:11]
	s_nop 7
	v_cndmask_b32_e64 v222, v8, v11, s[40:41]
	v_cndmask_b32_e64 v223, v9, v10, s[40:41]
	v_cndmask_b32_e64 v224, v10, v9, s[40:41]
	v_cndmask_b32_e64 v225, v11, v8, s[40:41]
	v_mul_f32_e32 v222, v222, v226
	v_mul_f32_e32 v223, v223, v226
	v_mul_f32_e32 v224, v224, v226
	v_mul_f32_e32 v225, v225, v226
	v_mul_f32_e32 v222, v80, v222
	v_mul_f32_e32 v223, v81, v223
	v_mul_f32_e32 v224, v82, v224
	v_mul_f32_e32 v225, v84, v225
	v_mul_f32_e32 v31, v222, v222
	v_fmac_f32_e32 v31, v223, v223
	v_fmac_f32_e32 v31, v224, v224
	v_fmac_f32_e32 v31, v225, v225
	v_add_f32_e32 v28, v28, v31
	s_mov_b64 exec, s[38:39]
	ds_write2_b32 v78, v222, v223 offset1:2
	ds_write2_b32 v78, v224, v225 offset0:4 offset1:6
	s_mov_b64 exec, -1
	v_add_u32_e32 v78, v78, v79
	s_waitcnt vmcnt(4)
	ds_bpermute_b32 v20, v30, v236
	ds_bpermute_b32 v21, v30, v237
	ds_bpermute_b32 v22, v30, v238
	ds_bpermute_b32 v23, v30, v239
	ds_bpermute_b32 v24, v30, v240
	ds_bpermute_b32 v25, v30, v241
	ds_bpermute_b32 v26, v30, v242
	ds_bpermute_b32 v27, v30, v243
	global_load_dwordx4 v[236:239], v85, s[70:71]
	global_load_dwordx4 v[240:243], v85, s[70:71] offset:64
	v_add_u32_e32 v85, 0x4000, v85
	v_add_u32_e32 v227, 0xc00, v29
	v_cvt_f32_i32_e32 v227, v227
	v_mul_f32_e32 v227, v93, v227
	v_mul_f32_e32 v227, 0x3fb8aa3b, v227
	v_exp_f32_e32 v226, v227
	s_waitcnt lgkmcnt(10)
	v_mfma_f32_16x16x32_f16 v[8:11], v[12:15], v[0:3], 0
	v_mfma_f32_16x16x32_f16 v[8:11], v[16:19], v[4:7], v[8:11]
	s_nop 7
	v_cndmask_b32_e64 v222, v8, v11, s[40:41]
	v_cndmask_b32_e64 v223, v9, v10, s[40:41]
	v_cndmask_b32_e64 v224, v10, v9, s[40:41]
	v_cndmask_b32_e64 v225, v11, v8, s[40:41]
	v_mul_f32_e32 v222, v222, v226
	v_mul_f32_e32 v223, v223, v226
	v_mul_f32_e32 v224, v224, v226
	v_mul_f32_e32 v225, v225, v226
	v_mul_f32_e32 v222, v80, v222
	v_mul_f32_e32 v223, v81, v223
	v_mul_f32_e32 v224, v82, v224
	v_mul_f32_e32 v225, v84, v225
	v_mul_f32_e32 v31, v222, v222
	v_fmac_f32_e32 v31, v223, v223
	v_fmac_f32_e32 v31, v224, v224
	v_fmac_f32_e32 v31, v225, v225
	v_add_f32_e32 v28, v28, v31
	s_mov_b64 exec, s[38:39]
	ds_write2_b32 v78, v222, v223 offset1:2
	ds_write2_b32 v78, v224, v225 offset0:4 offset1:6
	s_mov_b64 exec, -1
	v_add_u32_e32 v78, v78, v79
	s_waitcnt vmcnt(4)
	ds_bpermute_b32 v12, v30, v244
	ds_bpermute_b32 v13, v30, v245
	ds_bpermute_b32 v14, v30, v246
	ds_bpermute_b32 v15, v30, v247
	ds_bpermute_b32 v16, v30, v248
	ds_bpermute_b32 v17, v30, v249
	ds_bpermute_b32 v18, v30, v250
	ds_bpermute_b32 v19, v30, v251
	global_load_dwordx4 v[244:247], v85, s[70:71]
	global_load_dwordx4 v[248:251], v85, s[70:71] offset:64
	v_add_u32_e32 v85, 0x4000, v85
	v_add_u32_e32 v227, 0xc80, v29
	v_cvt_f32_i32_e32 v227, v227
	v_mul_f32_e32 v227, v93, v227
	v_mul_f32_e32 v227, 0x3fb8aa3b, v227
	v_exp_f32_e32 v226, v227
	s_waitcnt lgkmcnt(10)
	v_mfma_f32_16x16x32_f16 v[8:11], v[20:23], v[0:3], 0
	v_mfma_f32_16x16x32_f16 v[8:11], v[24:27], v[4:7], v[8:11]
	s_nop 7
	v_cndmask_b32_e64 v222, v8, v11, s[40:41]
	v_cndmask_b32_e64 v223, v9, v10, s[40:41]
	v_cndmask_b32_e64 v224, v10, v9, s[40:41]
	v_cndmask_b32_e64 v225, v11, v8, s[40:41]
	v_mul_f32_e32 v222, v222, v226
	v_mul_f32_e32 v223, v223, v226
	v_mul_f32_e32 v224, v224, v226
	v_mul_f32_e32 v225, v225, v226
	v_mul_f32_e32 v222, v80, v222
	v_mul_f32_e32 v223, v81, v223
	v_mul_f32_e32 v224, v82, v224
	v_mul_f32_e32 v225, v84, v225
	v_mul_f32_e32 v31, v222, v222
	v_fmac_f32_e32 v31, v223, v223
	v_fmac_f32_e32 v31, v224, v224
	v_fmac_f32_e32 v31, v225, v225
	v_add_f32_e32 v28, v28, v31
	s_mov_b64 exec, s[38:39]
	ds_write2_b32 v78, v222, v223 offset1:2
	ds_write2_b32 v78, v224, v225 offset0:4 offset1:6
	s_mov_b64 exec, -1
	v_add_u32_e32 v78, v78, v79
	s_waitcnt vmcnt(4)
	ds_bpermute_b32 v20, v30, v228
	ds_bpermute_b32 v21, v30, v229
	ds_bpermute_b32 v22, v30, v230
	ds_bpermute_b32 v23, v30, v231
	ds_bpermute_b32 v24, v30, v232
	ds_bpermute_b32 v25, v30, v233
	ds_bpermute_b32 v26, v30, v234
	ds_bpermute_b32 v27, v30, v235
	global_load_dwordx4 v[228:231], v85, s[70:71]
	global_load_dwordx4 v[232:235], v85, s[70:71] offset:64
	v_add_u32_e32 v85, 0x4000, v85
	v_add_u32_e32 v227, 0xd00, v29
	v_cvt_f32_i32_e32 v227, v227
	v_mul_f32_e32 v227, v93, v227
	v_mul_f32_e32 v227, 0x3fb8aa3b, v227
	v_exp_f32_e32 v226, v227
	s_waitcnt lgkmcnt(10)
; __device__ __forceinline__ void phase_hyena(KP kp_, int hf){ asm volatile("" : "+s"(kp_)); const Params p=load_params(kp_);
;     ...
;       _Pragma("unroll 8") for (int i=0;i<64;++i){ int tl=wid+8*i;
;         const _Float16* ap=a3+(size_t)(tl*16+n)*64+kg*8;
;         f16x8 a0=*(const f16x8*)ap, a1=*(const f16x8*)(ap+32);
;         f32x4 dd={0.f,0.f,0.f,0.f};
;         dd=__builtin_amdgcn_mfma_f32_16x16x32_f16(a0,bw0,dd,0,0,0);
;         dd=__builtin_amdgcn_mfma_f32_16x16x32_f16(a1,bw1,dd,0,0,0);
;         if (n<4){ float d0=__expf(dsc*(float)(tl*16)); int lag0=tl*16+kg*4;
;           float v0=dd[0]*d0*pj0, v1=dd[1]*d0*pj1, v2=dd[2]*d0*pj2, v3=dd[3]*d0*pj3;
;           if (!side1){ Zf[2*(lag0)+order]=v0; Zf[2*(lag0+1)+order]=v1; Zf[2*(lag0+2)+order]=v2; Zf[2*(lag0+3)+order]=v3; ssl+=v0*v0+v1*v1+v2*v2+v3*v3; }
;           else { if (lag0>=1){ Zf[2*(16384-lag0)+order]=v0; ssl+=v0*v0; }
;             Zf[2*(16384-lag0-1)+order]=v1; Zf[2*(16384-lag0-2)+order]=v2; Zf[2*(16384-lag0-3)+order]=v3; ssl+=v1*v1+v2*v2+v3*v3; } }
;       }
	v_mfma_f32_16x16x32_f16 v[8:11], v[12:15], v[0:3], 0
	v_mfma_f32_16x16x32_f16 v[8:11], v[16:19], v[4:7], v[8:11]
	s_nop 7
	v_cndmask_b32_e64 v222, v8, v11, s[40:41]
	v_cndmask_b32_e64 v223, v9, v10, s[40:41]
	v_cndmask_b32_e64 v224, v10, v9, s[40:41]
	v_cndmask_b32_e64 v225, v11, v8, s[40:41]
	v_mul_f32_e32 v222, v222, v226
	v_mul_f32_e32 v223, v223, v226
	v_mul_f32_e32 v224, v224, v226
	v_mul_f32_e32 v225, v225, v226
	v_mul_f32_e32 v222, v80, v222
	v_mul_f32_e32 v223, v81, v223
	v_mul_f32_e32 v224, v82, v224
	v_mul_f32_e32 v225, v84, v225
	v_mul_f32_e32 v31, v222, v222
	v_fmac_f32_e32 v31, v223, v223
	v_fmac_f32_e32 v31, v224, v224
	v_fmac_f32_e32 v31, v225, v225
	v_add_f32_e32 v28, v28, v31
	s_mov_b64 exec, s[38:39]
	ds_write2_b32 v78, v222, v223 offset1:2
	ds_write2_b32 v78, v224, v225 offset0:4 offset1:6
	s_mov_b64 exec, -1
	v_add_u32_e32 v78, v78, v79
	s_waitcnt vmcnt(4)
	ds_bpermute_b32 v12, v30, v236
	ds_bpermute_b32 v13, v30, v237
	ds_bpermute_b32 v14, v30, v238
	ds_bpermute_b32 v15, v30, v239
	ds_bpermute_b32 v16, v30, v240
	ds_bpermute_b32 v17, v30, v241
	ds_bpermute_b32 v18, v30, v242
	ds_bpermute_b32 v19, v30, v243
	global_load_dwordx4 v[236:239], v85, s[70:71]
	global_load_dwordx4 v[240:243], v85, s[70:71] offset:64
	v_add_u32_e32 v85, 0x4000, v85
	v_add_u32_e32 v227, 0xd80, v29
	v_cvt_f32_i32_e32 v227, v227
	v_mul_f32_e32 v227, v93, v227
	v_mul_f32_e32 v227, 0x3fb8aa3b, v227
	v_exp_f32_e32 v226, v227
	s_waitcnt lgkmcnt(10)
	v_mfma_f32_16x16x32_f16 v[8:11], v[20:23], v[0:3], 0
	v_mfma_f32_16x16x32_f16 v[8:11], v[24:27], v[4:7], v[8:11]
	s_nop 7
	v_cndmask_b32_e64 v222, v8, v11, s[40:41]
	v_cndmask_b32_e64 v223, v9, v10, s[40:41]
	v_cndmask_b32_e64 v224, v10, v9, s[40:41]
	v_cndmask_b32_e64 v225, v11, v8, s[40:41]
	v_mul_f32_e32 v222, v222, v226
	v_mul_f32_e32 v223, v223, v226
	v_mul_f32_e32 v224, v224, v226
	v_mul_f32_e32 v225, v225, v226
	v_mul_f32_e32 v222, v80, v222
	v_mul_f32_e32 v223, v81, v223
	v_mul_f32_e32 v224, v82, v224
	v_mul_f32_e32 v225, v84, v225
	v_mul_f32_e32 v31, v222, v222
	v_fmac_f32_e32 v31, v223, v223
	v_fmac_f32_e32 v31, v224, v224
	v_fmac_f32_e32 v31, v225, v225
	v_add_f32_e32 v28, v28, v31
	s_mov_b64 exec, s[38:39]
	ds_write2_b32 v78, v222, v223 offset1:2
	ds_write2_b32 v78, v224, v225 offset0:4 offset1:6
	s_mov_b64 exec, -1
	v_add_u32_e32 v78, v78, v79
	s_waitcnt vmcnt(4)
	ds_bpermute_b32 v20, v30, v244
	ds_bpermute_b32 v21, v30, v245
	ds_bpermute_b32 v22, v30, v246
	ds_bpermute_b32 v23, v30, v247
	ds_bpermute_b32 v24, v30, v248
	ds_bpermute_b32 v25, v30, v249
	ds_bpermute_b32 v26, v30, v250
	ds_bpermute_b32 v27, v30, v251
	global_load_dwordx4 v[244:247], v85, s[70:71]
	global_load_dwordx4 v[248:251], v85, s[70:71] offset:64
	v_add_u32_e32 v85, 0x4000, v85
	v_add_u32_e32 v227, 0xe00, v29
	v_cvt_f32_i32_e32 v227, v227
	v_mul_f32_e32 v227, v93, v227
	v_mul_f32_e32 v227, 0x3fb8aa3b, v227
	v_exp_f32_e32 v226, v227
	s_waitcnt lgkmcnt(10)
	v_mfma_f32_16x16x32_f16 v[8:11], v[12:15], v[0:3], 0
	v_mfma_f32_16x16x32_f16 v[8:11], v[16:19], v[4:7], v[8:11]
	s_nop 7
	v_cndmask_b32_e64 v222, v8, v11, s[40:41]
	v_cndmask_b32_e64 v223, v9, v10, s[40:41]
	v_cndmask_b32_e64 v224, v10, v9, s[40:41]
	v_cndmask_b32_e64 v225, v11, v8, s[40:41]
	v_mul_f32_e32 v222, v222, v226
	v_mul_f32_e32 v223, v223, v226
	v_mul_f32_e32 v224, v224, v226
	v_mul_f32_e32 v225, v225, v226
	v_mul_f32_e32 v222, v80, v222
	v_mul_f32_e32 v223, v81, v223
	v_mul_f32_e32 v224, v82, v224
	v_mul_f32_e32 v225, v84, v225
	v_mul_f32_e32 v31, v222, v222
	v_fmac_f32_e32 v31, v223, v223
	v_fmac_f32_e32 v31, v224, v224
	v_fmac_f32_e32 v31, v225, v225
	v_add_f32_e32 v28, v28, v31
	s_mov_b64 exec, s[38:39]
	ds_write2_b32 v78, v222, v223 offset1:2
	ds_write2_b32 v78, v224, v225 offset0:4 offset1:6
	s_mov_b64 exec, -1
	v_add_u32_e32 v78, v78, v79
	s_waitcnt vmcnt(4)
	ds_bpermute_b32 v12, v30, v228
	ds_bpermute_b32 v13, v30, v229
	ds_bpermute_b32 v14, v30, v230
	ds_bpermute_b32 v15, v30, v231
	ds_bpermute_b32 v16, v30, v232
	ds_bpermute_b32 v17, v30, v233
	ds_bpermute_b32 v18, v30, v234
	ds_bpermute_b32 v19, v30, v235
	global_load_dwordx4 v[228:231], v85, s[70:71]
	global_load_dwordx4 v[232:235], v85, s[70:71] offset:64
	v_add_u32_e32 v85, 0x4000, v85
	v_add_u32_e32 v227, 0xe80, v29
	v_cvt_f32_i32_e32 v227, v227
	v_mul_f32_e32 v227, v93, v227
	v_mul_f32_e32 v227, 0x3fb8aa3b, v227
	v_exp_f32_e32 v226, v227
	s_waitcnt lgkmcnt(10)
	v_mfma_f32_16x16x32_f16 v[8:11], v[20:23], v[0:3], 0
	v_mfma_f32_16x16x32_f16 v[8:11], v[24:27], v[4:7], v[8:11]
	s_nop 7
	v_cndmask_b32_e64 v222, v8, v11, s[40:41]
	v_cndmask_b32_e64 v223, v9, v10, s[40:41]
	v_cndmask_b32_e64 v224, v10, v9, s[40:41]
	v_cndmask_b32_e64 v225, v11, v8, s[40:41]
	v_mul_f32_e32 v222, v222, v226
	v_mul_f32_e32 v223, v223, v226
	v_mul_f32_e32 v224, v224, v226
	v_mul_f32_e32 v225, v225, v226
	v_mul_f32_e32 v222, v80, v222
	v_mul_f32_e32 v223, v81, v223
	v_mul_f32_e32 v224, v82, v224
	v_mul_f32_e32 v225, v84, v225
	v_mul_f32_e32 v31, v222, v222
	v_fmac_f32_e32 v31, v223, v223
	v_fmac_f32_e32 v31, v224, v224
	v_fmac_f32_e32 v31, v225, v225
	v_add_f32_e32 v28, v28, v31
	s_mov_b64 exec, s[38:39]
	ds_write2_b32 v78, v222, v223 offset1:2
	ds_write2_b32 v78, v224, v225 offset0:4 offset1:6
	s_mov_b64 exec, -1
	v_add_u32_e32 v78, v78, v79
	s_waitcnt vmcnt(4)
	ds_bpermute_b32 v20, v30, v236
	ds_bpermute_b32 v21, v30, v237
	ds_bpermute_b32 v22, v30, v238
	ds_bpermute_b32 v23, v30, v239
	ds_bpermute_b32 v24, v30, v240
	ds_bpermute_b32 v25, v30, v241
	ds_bpermute_b32 v26, v30, v242
	ds_bpermute_b32 v27, v30, v243
	global_load_dwordx4 v[236:239], v85, s[70:71]
	global_load_dwordx4 v[240:243], v85, s[70:71] offset:64
	v_add_u32_e32 v85, 0x4000, v85
	v_add_u32_e32 v227, 0xf00, v29
	v_cvt_f32_i32_e32 v227, v227
	v_mul_f32_e32 v227, v93, v227
	v_mul_f32_e32 v227, 0x3fb8aa3b, v227
	v_exp_f32_e32 v226, v227
	s_waitcnt lgkmcnt(10)
; __device__ __forceinline__ void phase_hyena(KP kp_, int hf){ asm volatile("" : "+s"(kp_)); const Params p=load_params(kp_);
;     ...
;       _Pragma("unroll 8") for (int i=0;i<64;++i){ int tl=wid+8*i;
;         const _Float16* ap=a3+(size_t)(tl*16+n)*64+kg*8;
;         f16x8 a0=*(const f16x8*)ap, a1=*(const f16x8*)(ap+32);
;         f32x4 dd={0.f,0.f,0.f,0.f};
;         dd=__builtin_amdgcn_mfma_f32_16x16x32_f16(a0,bw0,dd,0,0,0);
;         dd=__builtin_amdgcn_mfma_f32_16x16x32_f16(a1,bw1,dd,0,0,0);
;         if (n<4){ float d0=__expf(dsc*(float)(tl*16)); int lag0=tl*16+kg*4;
;           float v0=dd[0]*d0*pj0, v1=dd[1]*d0*pj1, v2=dd[2]*d0*pj2, v3=dd[3]*d0*pj3;
;           if (!side1){ Zf[2*(lag0)+order]=v0; Zf[2*(lag0+1)+order]=v1; Zf[2*(lag0+2)+order]=v2; Zf[2*(lag0+3)+order]=v3; ssl+=v0*v0+v1*v1+v2*v2+v3*v3; }
;           else { if (lag0>=1){ Zf[2*(16384-lag0)+order]=v0; ssl+=v0*v0; }
;             Zf[2*(16384-lag0-1)+order]=v1; Zf[2*(16384-lag0-2)+order]=v2; Zf[2*(16384-lag0-3)+order]=v3; ssl+=v1*v1+v2*v2+v3*v3; } }
;       }
	v_mfma_f32_16x16x32_f16 v[8:11], v[12:15], v[0:3], 0
	v_mfma_f32_16x16x32_f16 v[8:11], v[16:19], v[4:7], v[8:11]
	s_nop 7
	v_cndmask_b32_e64 v222, v8, v11, s[40:41]
	v_cndmask_b32_e64 v223, v9, v10, s[40:41]
	v_cndmask_b32_e64 v224, v10, v9, s[40:41]
	v_cndmask_b32_e64 v225, v11, v8, s[40:41]
	v_mul_f32_e32 v222, v222, v226
	v_mul_f32_e32 v223, v223, v226
	v_mul_f32_e32 v224, v224, v226
	v_mul_f32_e32 v225, v225, v226
	v_mul_f32_e32 v222, v80, v222
	v_mul_f32_e32 v223, v81, v223
	v_mul_f32_e32 v224, v82, v224
	v_mul_f32_e32 v225, v84, v225
	v_mul_f32_e32 v31, v222, v222
	v_fmac_f32_e32 v31, v223, v223
	v_fmac_f32_e32 v31, v224, v224
	v_fmac_f32_e32 v31, v225, v225
	v_add_f32_e32 v28, v28, v31
	s_mov_b64 exec, s[38:39]
	ds_write2_b32 v78, v222, v223 offset1:2
	ds_write2_b32 v78, v224, v225 offset0:4 offset1:6
	s_mov_b64 exec, -1
	v_add_u32_e32 v78, v78, v79
	s_waitcnt vmcnt(4)
	ds_bpermute_b32 v12, v30, v244
	ds_bpermute_b32 v13, v30, v245
	ds_bpermute_b32 v14, v30, v246
	ds_bpermute_b32 v15, v30, v247
	ds_bpermute_b32 v16, v30, v248
	ds_bpermute_b32 v17, v30, v249
	ds_bpermute_b32 v18, v30, v250
	ds_bpermute_b32 v19, v30, v251
	global_load_dwordx4 v[244:247], v85, s[70:71]
	global_load_dwordx4 v[248:251], v85, s[70:71] offset:64
	v_add_u32_e32 v85, 0x4000, v85
	v_add_u32_e32 v227, 0xf80, v29
	v_cvt_f32_i32_e32 v227, v227
	v_mul_f32_e32 v227, v93, v227
	v_mul_f32_e32 v227, 0x3fb8aa3b, v227
	v_exp_f32_e32 v226, v227
	s_waitcnt lgkmcnt(10)
	v_mfma_f32_16x16x32_f16 v[8:11], v[20:23], v[0:3], 0
	v_mfma_f32_16x16x32_f16 v[8:11], v[24:27], v[4:7], v[8:11]
	s_nop 7
	v_cndmask_b32_e64 v222, v8, v11, s[40:41]
	v_cndmask_b32_e64 v223, v9, v10, s[40:41]
	v_cndmask_b32_e64 v224, v10, v9, s[40:41]
	v_cndmask_b32_e64 v225, v11, v8, s[40:41]
	v_mul_f32_e32 v222, v222, v226
	v_mul_f32_e32 v223, v223, v226
	v_mul_f32_e32 v224, v224, v226
	v_mul_f32_e32 v225, v225, v226
	v_mul_f32_e32 v222, v80, v222
	v_mul_f32_e32 v223, v81, v223
	v_mul_f32_e32 v224, v82, v224
	v_mul_f32_e32 v225, v84, v225
	v_mul_f32_e32 v31, v222, v222
	v_fmac_f32_e32 v31, v223, v223
	v_fmac_f32_e32 v31, v224, v224
	v_fmac_f32_e32 v31, v225, v225
	v_add_f32_e32 v28, v28, v31
	s_mov_b64 exec, s[38:39]
	ds_write2_b32 v78, v222, v223 offset1:2
	ds_write2_b32 v78, v224, v225 offset0:4 offset1:6
	s_mov_b64 exec, -1
	v_add_u32_e32 v78, v78, v79
	s_waitcnt vmcnt(4)
	ds_bpermute_b32 v20, v30, v228
	ds_bpermute_b32 v21, v30, v229
	ds_bpermute_b32 v22, v30, v230
	ds_bpermute_b32 v23, v30, v231
	ds_bpermute_b32 v24, v30, v232
	ds_bpermute_b32 v25, v30, v233
	ds_bpermute_b32 v26, v30, v234
	ds_bpermute_b32 v27, v30, v235
	global_load_dwordx4 v[228:231], v85, s[70:71]
	global_load_dwordx4 v[232:235], v85, s[70:71] offset:64
	v_add_u32_e32 v85, 0x4000, v85
	v_add_u32_e32 v227, 0x1000, v29
	v_cvt_f32_i32_e32 v227, v227
	v_mul_f32_e32 v227, v93, v227
	v_mul_f32_e32 v227, 0x3fb8aa3b, v227
	v_exp_f32_e32 v226, v227
	s_waitcnt lgkmcnt(10)
	v_mfma_f32_16x16x32_f16 v[8:11], v[12:15], v[0:3], 0
	v_mfma_f32_16x16x32_f16 v[8:11], v[16:19], v[4:7], v[8:11]
	s_nop 7
	v_cndmask_b32_e64 v222, v8, v11, s[40:41]
	v_cndmask_b32_e64 v223, v9, v10, s[40:41]
	v_cndmask_b32_e64 v224, v10, v9, s[40:41]
	v_cndmask_b32_e64 v225, v11, v8, s[40:41]
	v_mul_f32_e32 v222, v222, v226
	v_mul_f32_e32 v223, v223, v226
	v_mul_f32_e32 v224, v224, v226
	v_mul_f32_e32 v225, v225, v226
	v_mul_f32_e32 v222, v80, v222
	v_mul_f32_e32 v223, v81, v223
	v_mul_f32_e32 v224, v82, v224
	v_mul_f32_e32 v225, v84, v225
	v_mul_f32_e32 v31, v222, v222
	v_fmac_f32_e32 v31, v223, v223
	v_fmac_f32_e32 v31, v224, v224
	v_fmac_f32_e32 v31, v225, v225
	v_add_f32_e32 v28, v28, v31
	s_mov_b64 exec, s[38:39]
	ds_write2_b32 v78, v222, v223 offset1:2
	ds_write2_b32 v78, v224, v225 offset0:4 offset1:6
	s_mov_b64 exec, -1
	v_add_u32_e32 v78, v78, v79
	s_waitcnt vmcnt(4)
	ds_bpermute_b32 v12, v30, v236
	ds_bpermute_b32 v13, v30, v237
	ds_bpermute_b32 v14, v30, v238
	ds_bpermute_b32 v15, v30, v239
	ds_bpermute_b32 v16, v30, v240
	ds_bpermute_b32 v17, v30, v241
	ds_bpermute_b32 v18, v30, v242
	ds_bpermute_b32 v19, v30, v243
	global_load_dwordx4 v[236:239], v85, s[70:71]
	global_load_dwordx4 v[240:243], v85, s[70:71] offset:64
	v_add_u32_e32 v85, 0x4000, v85
	v_add_u32_e32 v227, 0x1080, v29
	v_cvt_f32_i32_e32 v227, v227
	v_mul_f32_e32 v227, v93, v227
	v_mul_f32_e32 v227, 0x3fb8aa3b, v227
	v_exp_f32_e32 v226, v227
	s_waitcnt lgkmcnt(10)
	v_mfma_f32_16x16x32_f16 v[8:11], v[20:23], v[0:3], 0
	v_mfma_f32_16x16x32_f16 v[8:11], v[24:27], v[4:7], v[8:11]
	s_nop 7
	v_cndmask_b32_e64 v222, v8, v11, s[40:41]
	v_cndmask_b32_e64 v223, v9, v10, s[40:41]
	v_cndmask_b32_e64 v224, v10, v9, s[40:41]
	v_cndmask_b32_e64 v225, v11, v8, s[40:41]
	v_mul_f32_e32 v222, v222, v226
	v_mul_f32_e32 v223, v223, v226
	v_mul_f32_e32 v224, v224, v226
	v_mul_f32_e32 v225, v225, v226
	v_mul_f32_e32 v222, v80, v222
	v_mul_f32_e32 v223, v81, v223
	v_mul_f32_e32 v224, v82, v224
	v_mul_f32_e32 v225, v84, v225
	v_mul_f32_e32 v31, v222, v222
	v_fmac_f32_e32 v31, v223, v223
	v_fmac_f32_e32 v31, v224, v224
	v_fmac_f32_e32 v31, v225, v225
	v_add_f32_e32 v28, v28, v31
	s_mov_b64 exec, s[38:39]
	ds_write2_b32 v78, v222, v223 offset1:2
	ds_write2_b32 v78, v224, v225 offset0:4 offset1:6
	s_mov_b64 exec, -1
	v_add_u32_e32 v78, v78, v79
	s_waitcnt vmcnt(4)
	ds_bpermute_b32 v20, v30, v244
	ds_bpermute_b32 v21, v30, v245
	ds_bpermute_b32 v22, v30, v246
	ds_bpermute_b32 v23, v30, v247
	ds_bpermute_b32 v24, v30, v248
	ds_bpermute_b32 v25, v30, v249
	ds_bpermute_b32 v26, v30, v250
	ds_bpermute_b32 v27, v30, v251
	global_load_dwordx4 v[244:247], v85, s[70:71]
	global_load_dwordx4 v[248:251], v85, s[70:71] offset:64
	v_add_u32_e32 v85, 0x4000, v85
	v_add_u32_e32 v227, 0x1100, v29
	v_cvt_f32_i32_e32 v227, v227
	v_mul_f32_e32 v227, v93, v227
	v_mul_f32_e32 v227, 0x3fb8aa3b, v227
	v_exp_f32_e32 v226, v227
	s_waitcnt lgkmcnt(10)
; __device__ __forceinline__ void phase_hyena(KP kp_, int hf){ asm volatile("" : "+s"(kp_)); const Params p=load_params(kp_);
;     ...
;       _Pragma("unroll 8") for (int i=0;i<64;++i){ int tl=wid+8*i;
;         const _Float16* ap=a3+(size_t)(tl*16+n)*64+kg*8;
;         f16x8 a0=*(const f16x8*)ap, a1=*(const f16x8*)(ap+32);
;         f32x4 dd={0.f,0.f,0.f,0.f};
;         dd=__builtin_amdgcn_mfma_f32_16x16x32_f16(a0,bw0,dd,0,0,0);
;         dd=__builtin_amdgcn_mfma_f32_16x16x32_f16(a1,bw1,dd,0,0,0);
;         if (n<4){ float d0=__expf(dsc*(float)(tl*16)); int lag0=tl*16+kg*4;
;           float v0=dd[0]*d0*pj0, v1=dd[1]*d0*pj1, v2=dd[2]*d0*pj2, v3=dd[3]*d0*pj3;
;           if (!side1){ Zf[2*(lag0)+order]=v0; Zf[2*(lag0+1)+order]=v1; Zf[2*(lag0+2)+order]=v2; Zf[2*(lag0+3)+order]=v3; ssl+=v0*v0+v1*v1+v2*v2+v3*v3; }
;           else { if (lag0>=1){ Zf[2*(16384-lag0)+order]=v0; ssl+=v0*v0; }
;             Zf[2*(16384-lag0-1)+order]=v1; Zf[2*(16384-lag0-2)+order]=v2; Zf[2*(16384-lag0-3)+order]=v3; ssl+=v1*v1+v2*v2+v3*v3; } }
;       }
	v_mfma_f32_16x16x32_f16 v[8:11], v[12:15], v[0:3], 0
	v_mfma_f32_16x16x32_f16 v[8:11], v[16:19], v[4:7], v[8:11]
	s_nop 7
	v_cndmask_b32_e64 v222, v8, v11, s[40:41]
	v_cndmask_b32_e64 v223, v9, v10, s[40:41]
	v_cndmask_b32_e64 v224, v10, v9, s[40:41]
	v_cndmask_b32_e64 v225, v11, v8, s[40:41]
	v_mul_f32_e32 v222, v222, v226
	v_mul_f32_e32 v223, v223, v226
	v_mul_f32_e32 v224, v224, v226
	v_mul_f32_e32 v225, v225, v226
	v_mul_f32_e32 v222, v80, v222
	v_mul_f32_e32 v223, v81, v223
	v_mul_f32_e32 v224, v82, v224
	v_mul_f32_e32 v225, v84, v225
	v_mul_f32_e32 v31, v222, v222
	v_fmac_f32_e32 v31, v223, v223
	v_fmac_f32_e32 v31, v224, v224
	v_fmac_f32_e32 v31, v225, v225
	v_add_f32_e32 v28, v28, v31
	s_mov_b64 exec, s[38:39]
	ds_write2_b32 v78, v222, v223 offset1:2
	ds_write2_b32 v78, v224, v225 offset0:4 offset1:6
	s_mov_b64 exec, -1
	v_add_u32_e32 v78, v78, v79
	s_waitcnt vmcnt(4)
	ds_bpermute_b32 v12, v30, v228
	ds_bpermute_b32 v13, v30, v229
	ds_bpermute_b32 v14, v30, v230
	ds_bpermute_b32 v15, v30, v231
	ds_bpermute_b32 v16, v30, v232
	ds_bpermute_b32 v17, v30, v233
	ds_bpermute_b32 v18, v30, v234
	ds_bpermute_b32 v19, v30, v235
	global_load_dwordx4 v[228:231], v85, s[70:71]
	global_load_dwordx4 v[232:235], v85, s[70:71] offset:64
	v_add_u32_e32 v85, 0x4000, v85
	v_add_u32_e32 v227, 0x1180, v29
	v_cvt_f32_i32_e32 v227, v227
	v_mul_f32_e32 v227, v93, v227
	v_mul_f32_e32 v227, 0x3fb8aa3b, v227
	v_exp_f32_e32 v226, v227
	s_waitcnt lgkmcnt(10)
	v_mfma_f32_16x16x32_f16 v[8:11], v[20:23], v[0:3], 0
	v_mfma_f32_16x16x32_f16 v[8:11], v[24:27], v[4:7], v[8:11]
	s_nop 7
	v_cndmask_b32_e64 v222, v8, v11, s[40:41]
	v_cndmask_b32_e64 v223, v9, v10, s[40:41]
	v_cndmask_b32_e64 v224, v10, v9, s[40:41]
	v_cndmask_b32_e64 v225, v11, v8, s[40:41]
	v_mul_f32_e32 v222, v222, v226
	v_mul_f32_e32 v223, v223, v226
	v_mul_f32_e32 v224, v224, v226
	v_mul_f32_e32 v225, v225, v226
	v_mul_f32_e32 v222, v80, v222
	v_mul_f32_e32 v223, v81, v223
	v_mul_f32_e32 v224, v82, v224
	v_mul_f32_e32 v225, v84, v225
	v_mul_f32_e32 v31, v222, v222
	v_fmac_f32_e32 v31, v223, v223
	v_fmac_f32_e32 v31, v224, v224
	v_fmac_f32_e32 v31, v225, v225
	v_add_f32_e32 v28, v28, v31
	s_mov_b64 exec, s[38:39]
	ds_write2_b32 v78, v222, v223 offset1:2
	ds_write2_b32 v78, v224, v225 offset0:4 offset1:6
	s_mov_b64 exec, -1
	v_add_u32_e32 v78, v78, v79
	s_waitcnt vmcnt(4)
	ds_bpermute_b32 v20, v30, v236
	ds_bpermute_b32 v21, v30, v237
	ds_bpermute_b32 v22, v30, v238
	ds_bpermute_b32 v23, v30, v239
	ds_bpermute_b32 v24, v30, v240
	ds_bpermute_b32 v25, v30, v241
	ds_bpermute_b32 v26, v30, v242
	ds_bpermute_b32 v27, v30, v243
	global_load_dwordx4 v[236:239], v85, s[70:71]
	global_load_dwordx4 v[240:243], v85, s[70:71] offset:64
	v_add_u32_e32 v85, 0x4000, v85
	v_add_u32_e32 v227, 0x1200, v29
	v_cvt_f32_i32_e32 v227, v227
	v_mul_f32_e32 v227, v93, v227
	v_mul_f32_e32 v227, 0x3fb8aa3b, v227
	v_exp_f32_e32 v226, v227
	s_waitcnt lgkmcnt(10)
	v_mfma_f32_16x16x32_f16 v[8:11], v[12:15], v[0:3], 0
	v_mfma_f32_16x16x32_f16 v[8:11], v[16:19], v[4:7], v[8:11]
	s_nop 7
	v_cndmask_b32_e64 v222, v8, v11, s[40:41]
	v_cndmask_b32_e64 v223, v9, v10, s[40:41]
	v_cndmask_b32_e64 v224, v10, v9, s[40:41]
	v_cndmask_b32_e64 v225, v11, v8, s[40:41]
	v_mul_f32_e32 v222, v222, v226
	v_mul_f32_e32 v223, v223, v226
	v_mul_f32_e32 v224, v224, v226
	v_mul_f32_e32 v225, v225, v226
	v_mul_f32_e32 v222, v80, v222
	v_mul_f32_e32 v223, v81, v223
	v_mul_f32_e32 v224, v82, v224
	v_mul_f32_e32 v225, v84, v225
	v_mul_f32_e32 v31, v222, v222
	v_fmac_f32_e32 v31, v223, v223
	v_fmac_f32_e32 v31, v224, v224
	v_fmac_f32_e32 v31, v225, v225
	v_add_f32_e32 v28, v28, v31
	s_mov_b64 exec, s[38:39]
	ds_write2_b32 v78, v222, v223 offset1:2
	ds_write2_b32 v78, v224, v225 offset0:4 offset1:6
	s_mov_b64 exec, -1
	v_add_u32_e32 v78, v78, v79
	s_waitcnt vmcnt(4)
	ds_bpermute_b32 v12, v30, v244
	ds_bpermute_b32 v13, v30, v245
	ds_bpermute_b32 v14, v30, v246
	ds_bpermute_b32 v15, v30, v247
	ds_bpermute_b32 v16, v30, v248
	ds_bpermute_b32 v17, v30, v249
	ds_bpermute_b32 v18, v30, v250
	ds_bpermute_b32 v19, v30, v251
	global_load_dwordx4 v[244:247], v85, s[70:71]
	global_load_dwordx4 v[248:251], v85, s[70:71] offset:64
	v_add_u32_e32 v85, 0x4000, v85
	v_add_u32_e32 v227, 0x1280, v29
	v_cvt_f32_i32_e32 v227, v227
	v_mul_f32_e32 v227, v93, v227
	v_mul_f32_e32 v227, 0x3fb8aa3b, v227
	v_exp_f32_e32 v226, v227
	s_waitcnt lgkmcnt(10)
	v_mfma_f32_16x16x32_f16 v[8:11], v[20:23], v[0:3], 0
	v_mfma_f32_16x16x32_f16 v[8:11], v[24:27], v[4:7], v[8:11]
	s_nop 7
	v_cndmask_b32_e64 v222, v8, v11, s[40:41]
	v_cndmask_b32_e64 v223, v9, v10, s[40:41]
	v_cndmask_b32_e64 v224, v10, v9, s[40:41]
	v_cndmask_b32_e64 v225, v11, v8, s[40:41]
	v_mul_f32_e32 v222, v222, v226
	v_mul_f32_e32 v223, v223, v226
	v_mul_f32_e32 v224, v224, v226
	v_mul_f32_e32 v225, v225, v226
	v_mul_f32_e32 v222, v80, v222
	v_mul_f32_e32 v223, v81, v223
	v_mul_f32_e32 v224, v82, v224
	v_mul_f32_e32 v225, v84, v225
	v_mul_f32_e32 v31, v222, v222
	v_fmac_f32_e32 v31, v223, v223
	v_fmac_f32_e32 v31, v224, v224
	v_fmac_f32_e32 v31, v225, v225
	v_add_f32_e32 v28, v28, v31
	s_mov_b64 exec, s[38:39]
	ds_write2_b32 v78, v222, v223 offset1:2
	ds_write2_b32 v78, v224, v225 offset0:4 offset1:6
	s_mov_b64 exec, -1
	v_add_u32_e32 v78, v78, v79
	s_waitcnt vmcnt(4)
	ds_bpermute_b32 v20, v30, v228
	ds_bpermute_b32 v21, v30, v229
	ds_bpermute_b32 v22, v30, v230
	ds_bpermute_b32 v23, v30, v231
	ds_bpermute_b32 v24, v30, v232
	ds_bpermute_b32 v25, v30, v233
	ds_bpermute_b32 v26, v30, v234
	ds_bpermute_b32 v27, v30, v235
	global_load_dwordx4 v[228:231], v85, s[70:71]
	global_load_dwordx4 v[232:235], v85, s[70:71] offset:64
	v_add_u32_e32 v85, 0x4000, v85
	v_add_u32_e32 v227, 0x1300, v29
	v_cvt_f32_i32_e32 v227, v227
	v_mul_f32_e32 v227, v93, v227
	v_mul_f32_e32 v227, 0x3fb8aa3b, v227
	v_exp_f32_e32 v226, v227
	s_waitcnt lgkmcnt(10)
; __device__ __forceinline__ void phase_hyena(KP kp_, int hf){ asm volatile("" : "+s"(kp_)); const Params p=load_params(kp_);
;     ...
;       _Pragma("unroll 8") for (int i=0;i<64;++i){ int tl=wid+8*i;
;         const _Float16* ap=a3+(size_t)(tl*16+n)*64+kg*8;
;         f16x8 a0=*(const f16x8*)ap, a1=*(const f16x8*)(ap+32);
;         f32x4 dd={0.f,0.f,0.f,0.f};
;         dd=__builtin_amdgcn_mfma_f32_16x16x32_f16(a0,bw0,dd,0,0,0);
;         dd=__builtin_amdgcn_mfma_f32_16x16x32_f16(a1,bw1,dd,0,0,0);
;         if (n<4){ float d0=__expf(dsc*(float)(tl*16)); int lag0=tl*16+kg*4;
;           float v0=dd[0]*d0*pj0, v1=dd[1]*d0*pj1, v2=dd[2]*d0*pj2, v3=dd[3]*d0*pj3;
;           if (!side1){ Zf[2*(lag0)+order]=v0; Zf[2*(lag0+1)+order]=v1; Zf[2*(lag0+2)+order]=v2; Zf[2*(lag0+3)+order]=v3; ssl+=v0*v0+v1*v1+v2*v2+v3*v3; }
;           else { if (lag0>=1){ Zf[2*(16384-lag0)+order]=v0; ssl+=v0*v0; }
;             Zf[2*(16384-lag0-1)+order]=v1; Zf[2*(16384-lag0-2)+order]=v2; Zf[2*(16384-lag0-3)+order]=v3; ssl+=v1*v1+v2*v2+v3*v3; } }
;       }
	v_mfma_f32_16x16x32_f16 v[8:11], v[12:15], v[0:3], 0
	v_mfma_f32_16x16x32_f16 v[8:11], v[16:19], v[4:7], v[8:11]
	s_nop 7
	v_cndmask_b32_e64 v222, v8, v11, s[40:41]
	v_cndmask_b32_e64 v223, v9, v10, s[40:41]
	v_cndmask_b32_e64 v224, v10, v9, s[40:41]
	v_cndmask_b32_e64 v225, v11, v8, s[40:41]
	v_mul_f32_e32 v222, v222, v226
	v_mul_f32_e32 v223, v223, v226
	v_mul_f32_e32 v224, v224, v226
	v_mul_f32_e32 v225, v225, v226
	v_mul_f32_e32 v222, v80, v222
	v_mul_f32_e32 v223, v81, v223
	v_mul_f32_e32 v224, v82, v224
	v_mul_f32_e32 v225, v84, v225
	v_mul_f32_e32 v31, v222, v222
	v_fmac_f32_e32 v31, v223, v223
	v_fmac_f32_e32 v31, v224, v224
	v_fmac_f32_e32 v31, v225, v225
	v_add_f32_e32 v28, v28, v31
	s_mov_b64 exec, s[38:39]
	ds_write2_b32 v78, v222, v223 offset1:2
	ds_write2_b32 v78, v224, v225 offset0:4 offset1:6
	s_mov_b64 exec, -1
	v_add_u32_e32 v78, v78, v79
	s_waitcnt vmcnt(4)
	ds_bpermute_b32 v12, v30, v236
	ds_bpermute_b32 v13, v30, v237
	ds_bpermute_b32 v14, v30, v238
	ds_bpermute_b32 v15, v30, v239
	ds_bpermute_b32 v16, v30, v240
	ds_bpermute_b32 v17, v30, v241
	ds_bpermute_b32 v18, v30, v242
	ds_bpermute_b32 v19, v30, v243
	global_load_dwordx4 v[236:239], v85, s[70:71]
	global_load_dwordx4 v[240:243], v85, s[70:71] offset:64
	v_add_u32_e32 v85, 0x4000, v85
	v_add_u32_e32 v227, 0x1380, v29
	v_cvt_f32_i32_e32 v227, v227
	v_mul_f32_e32 v227, v93, v227
	v_mul_f32_e32 v227, 0x3fb8aa3b, v227
	v_exp_f32_e32 v226, v227
	s_waitcnt lgkmcnt(10)
	v_mfma_f32_16x16x32_f16 v[8:11], v[20:23], v[0:3], 0
	v_mfma_f32_16x16x32_f16 v[8:11], v[24:27], v[4:7], v[8:11]
	s_nop 7
	v_cndmask_b32_e64 v222, v8, v11, s[40:41]
	v_cndmask_b32_e64 v223, v9, v10, s[40:41]
	v_cndmask_b32_e64 v224, v10, v9, s[40:41]
	v_cndmask_b32_e64 v225, v11, v8, s[40:41]
	v_mul_f32_e32 v222, v222, v226
	v_mul_f32_e32 v223, v223, v226
	v_mul_f32_e32 v224, v224, v226
	v_mul_f32_e32 v225, v225, v226
	v_mul_f32_e32 v222, v80, v222
	v_mul_f32_e32 v223, v81, v223
	v_mul_f32_e32 v224, v82, v224
	v_mul_f32_e32 v225, v84, v225
	v_mul_f32_e32 v31, v222, v222
	v_fmac_f32_e32 v31, v223, v223
	v_fmac_f32_e32 v31, v224, v224
	v_fmac_f32_e32 v31, v225, v225
	v_add_f32_e32 v28, v28, v31
	s_mov_b64 exec, s[38:39]
	ds_write2_b32 v78, v222, v223 offset1:2
	ds_write2_b32 v78, v224, v225 offset0:4 offset1:6
	s_mov_b64 exec, -1
	v_add_u32_e32 v78, v78, v79
	s_waitcnt vmcnt(4)
	ds_bpermute_b32 v20, v30, v244
	ds_bpermute_b32 v21, v30, v245
	ds_bpermute_b32 v22, v30, v246
	ds_bpermute_b32 v23, v30, v247
	ds_bpermute_b32 v24, v30, v248
	ds_bpermute_b32 v25, v30, v249
	ds_bpermute_b32 v26, v30, v250
	ds_bpermute_b32 v27, v30, v251
	global_load_dwordx4 v[244:247], v85, s[70:71]
	global_load_dwordx4 v[248:251], v85, s[70:71] offset:64
	v_add_u32_e32 v85, 0x4000, v85
	v_add_u32_e32 v227, 0x1400, v29
	v_cvt_f32_i32_e32 v227, v227
	v_mul_f32_e32 v227, v93, v227
	v_mul_f32_e32 v227, 0x3fb8aa3b, v227
	v_exp_f32_e32 v226, v227
	s_waitcnt lgkmcnt(10)
	v_mfma_f32_16x16x32_f16 v[8:11], v[12:15], v[0:3], 0
	v_mfma_f32_16x16x32_f16 v[8:11], v[16:19], v[4:7], v[8:11]
	s_nop 7
	v_cndmask_b32_e64 v222, v8, v11, s[40:41]
	v_cndmask_b32_e64 v223, v9, v10, s[40:41]
	v_cndmask_b32_e64 v224, v10, v9, s[40:41]
	v_cndmask_b32_e64 v225, v11, v8, s[40:41]
	v_mul_f32_e32 v222, v222, v226
	v_mul_f32_e32 v223, v223, v226
	v_mul_f32_e32 v224, v224, v226
	v_mul_f32_e32 v225, v225, v226
	v_mul_f32_e32 v222, v80, v222
	v_mul_f32_e32 v223, v81, v223
	v_mul_f32_e32 v224, v82, v224
	v_mul_f32_e32 v225, v84, v225
	v_mul_f32_e32 v31, v222, v222
	v_fmac_f32_e32 v31, v223, v223
	v_fmac_f32_e32 v31, v224, v224
	v_fmac_f32_e32 v31, v225, v225
	v_add_f32_e32 v28, v28, v31
	s_mov_b64 exec, s[38:39]
	ds_write2_b32 v78, v222, v223 offset1:2
	ds_write2_b32 v78, v224, v225 offset0:4 offset1:6
	s_mov_b64 exec, -1
	v_add_u32_e32 v78, v78, v79
	s_waitcnt vmcnt(4)
	ds_bpermute_b32 v12, v30, v228
	ds_bpermute_b32 v13, v30, v229
	ds_bpermute_b32 v14, v30, v230
	ds_bpermute_b32 v15, v30, v231
	ds_bpermute_b32 v16, v30, v232
	ds_bpermute_b32 v17, v30, v233
	ds_bpermute_b32 v18, v30, v234
	ds_bpermute_b32 v19, v30, v235
	global_load_dwordx4 v[228:231], v85, s[70:71]
	global_load_dwordx4 v[232:235], v85, s[70:71] offset:64
	v_add_u32_e32 v85, 0x4000, v85
	v_add_u32_e32 v227, 0x1480, v29
	v_cvt_f32_i32_e32 v227, v227
	v_mul_f32_e32 v227, v93, v227
	v_mul_f32_e32 v227, 0x3fb8aa3b, v227
	v_exp_f32_e32 v226, v227
	s_waitcnt lgkmcnt(10)
	v_mfma_f32_16x16x32_f16 v[8:11], v[20:23], v[0:3], 0
	v_mfma_f32_16x16x32_f16 v[8:11], v[24:27], v[4:7], v[8:11]
	s_nop 7
	v_cndmask_b32_e64 v222, v8, v11, s[40:41]
	v_cndmask_b32_e64 v223, v9, v10, s[40:41]
	v_cndmask_b32_e64 v224, v10, v9, s[40:41]
	v_cndmask_b32_e64 v225, v11, v8, s[40:41]
	v_mul_f32_e32 v222, v222, v226
	v_mul_f32_e32 v223, v223, v226
	v_mul_f32_e32 v224, v224, v226
	v_mul_f32_e32 v225, v225, v226
	v_mul_f32_e32 v222, v80, v222
	v_mul_f32_e32 v223, v81, v223
	v_mul_f32_e32 v224, v82, v224
	v_mul_f32_e32 v225, v84, v225
	v_mul_f32_e32 v31, v222, v222
	v_fmac_f32_e32 v31, v223, v223
	v_fmac_f32_e32 v31, v224, v224
	v_fmac_f32_e32 v31, v225, v225
	v_add_f32_e32 v28, v28, v31
	s_mov_b64 exec, s[38:39]
	ds_write2_b32 v78, v222, v223 offset1:2
	ds_write2_b32 v78, v224, v225 offset0:4 offset1:6
	s_mov_b64 exec, -1
	v_add_u32_e32 v78, v78, v79
	s_waitcnt vmcnt(4)
	ds_bpermute_b32 v20, v30, v236
	ds_bpermute_b32 v21, v30, v237
	ds_bpermute_b32 v22, v30, v238
	ds_bpermute_b32 v23, v30, v239
	ds_bpermute_b32 v24, v30, v240
	ds_bpermute_b32 v25, v30, v241
	ds_bpermute_b32 v26, v30, v242
	ds_bpermute_b32 v27, v30, v243
	global_load_dwordx4 v[236:239], v85, s[70:71]
	global_load_dwordx4 v[240:243], v85, s[70:71] offset:64
	v_add_u32_e32 v85, 0x4000, v85
	v_add_u32_e32 v227, 0x1500, v29
	v_cvt_f32_i32_e32 v227, v227
	v_mul_f32_e32 v227, v93, v227
	v_mul_f32_e32 v227, 0x3fb8aa3b, v227
	v_exp_f32_e32 v226, v227
	s_waitcnt lgkmcnt(10)
; __device__ __forceinline__ void phase_hyena(KP kp_, int hf){ asm volatile("" : "+s"(kp_)); const Params p=load_params(kp_);
;     ...
;       _Pragma("unroll 8") for (int i=0;i<64;++i){ int tl=wid+8*i;
;         const _Float16* ap=a3+(size_t)(tl*16+n)*64+kg*8;
;         f16x8 a0=*(const f16x8*)ap, a1=*(const f16x8*)(ap+32);
;         f32x4 dd={0.f,0.f,0.f,0.f};
;         dd=__builtin_amdgcn_mfma_f32_16x16x32_f16(a0,bw0,dd,0,0,0);
;         dd=__builtin_amdgcn_mfma_f32_16x16x32_f16(a1,bw1,dd,0,0,0);
;         if (n<4){ float d0=__expf(dsc*(float)(tl*16)); int lag0=tl*16+kg*4;
;           float v0=dd[0]*d0*pj0, v1=dd[1]*d0*pj1, v2=dd[2]*d0*pj2, v3=dd[3]*d0*pj3;
;           if (!side1){ Zf[2*(lag0)+order]=v0; Zf[2*(lag0+1)+order]=v1; Zf[2*(lag0+2)+order]=v2; Zf[2*(lag0+3)+order]=v3; ssl+=v0*v0+v1*v1+v2*v2+v3*v3; }
;           else { if (lag0>=1){ Zf[2*(16384-lag0)+order]=v0; ssl+=v0*v0; }
;             Zf[2*(16384-lag0-1)+order]=v1; Zf[2*(16384-lag0-2)+order]=v2; Zf[2*(16384-lag0-3)+order]=v3; ssl+=v1*v1+v2*v2+v3*v3; } }
;       }
	v_mfma_f32_16x16x32_f16 v[8:11], v[12:15], v[0:3], 0
	v_mfma_f32_16x16x32_f16 v[8:11], v[16:19], v[4:7], v[8:11]
	s_nop 7
	v_cndmask_b32_e64 v222, v8, v11, s[40:41]
	v_cndmask_b32_e64 v223, v9, v10, s[40:41]
	v_cndmask_b32_e64 v224, v10, v9, s[40:41]
	v_cndmask_b32_e64 v225, v11, v8, s[40:41]
	v_mul_f32_e32 v222, v222, v226
	v_mul_f32_e32 v223, v223, v226
	v_mul_f32_e32 v224, v224, v226
	v_mul_f32_e32 v225, v225, v226
	v_mul_f32_e32 v222, v80, v222
	v_mul_f32_e32 v223, v81, v223
	v_mul_f32_e32 v224, v82, v224
	v_mul_f32_e32 v225, v84, v225
	v_mul_f32_e32 v31, v222, v222
	v_fmac_f32_e32 v31, v223, v223
	v_fmac_f32_e32 v31, v224, v224
	v_fmac_f32_e32 v31, v225, v225
	v_add_f32_e32 v28, v28, v31
	s_mov_b64 exec, s[38:39]
	ds_write2_b32 v78, v222, v223 offset1:2
	ds_write2_b32 v78, v224, v225 offset0:4 offset1:6
	s_mov_b64 exec, -1
	v_add_u32_e32 v78, v78, v79
	s_waitcnt vmcnt(4)
	ds_bpermute_b32 v12, v30, v244
	ds_bpermute_b32 v13, v30, v245
	ds_bpermute_b32 v14, v30, v246
	ds_bpermute_b32 v15, v30, v247
	ds_bpermute_b32 v16, v30, v248
	ds_bpermute_b32 v17, v30, v249
	ds_bpermute_b32 v18, v30, v250
	ds_bpermute_b32 v19, v30, v251
	global_load_dwordx4 v[244:247], v85, s[70:71]
	global_load_dwordx4 v[248:251], v85, s[70:71] offset:64
	v_add_u32_e32 v85, 0x4000, v85
	v_add_u32_e32 v227, 0x1580, v29
	v_cvt_f32_i32_e32 v227, v227
	v_mul_f32_e32 v227, v93, v227
	v_mul_f32_e32 v227, 0x3fb8aa3b, v227
	v_exp_f32_e32 v226, v227
	s_waitcnt lgkmcnt(10)
	v_mfma_f32_16x16x32_f16 v[8:11], v[20:23], v[0:3], 0
	v_mfma_f32_16x16x32_f16 v[8:11], v[24:27], v[4:7], v[8:11]
	s_nop 7
	v_cndmask_b32_e64 v222, v8, v11, s[40:41]
	v_cndmask_b32_e64 v223, v9, v10, s[40:41]
	v_cndmask_b32_e64 v224, v10, v9, s[40:41]
	v_cndmask_b32_e64 v225, v11, v8, s[40:41]
	v_mul_f32_e32 v222, v222, v226
	v_mul_f32_e32 v223, v223, v226
	v_mul_f32_e32 v224, v224, v226
	v_mul_f32_e32 v225, v225, v226
	v_mul_f32_e32 v222, v80, v222
	v_mul_f32_e32 v223, v81, v223
	v_mul_f32_e32 v224, v82, v224
	v_mul_f32_e32 v225, v84, v225
	v_mul_f32_e32 v31, v222, v222
	v_fmac_f32_e32 v31, v223, v223
	v_fmac_f32_e32 v31, v224, v224
	v_fmac_f32_e32 v31, v225, v225
	v_add_f32_e32 v28, v28, v31
	s_mov_b64 exec, s[38:39]
	ds_write2_b32 v78, v222, v223 offset1:2
	ds_write2_b32 v78, v224, v225 offset0:4 offset1:6
	s_mov_b64 exec, -1
	v_add_u32_e32 v78, v78, v79
	s_waitcnt vmcnt(4)
	ds_bpermute_b32 v20, v30, v228
	ds_bpermute_b32 v21, v30, v229
	ds_bpermute_b32 v22, v30, v230
	ds_bpermute_b32 v23, v30, v231
	ds_bpermute_b32 v24, v30, v232
	ds_bpermute_b32 v25, v30, v233
	ds_bpermute_b32 v26, v30, v234
	ds_bpermute_b32 v27, v30, v235
	global_load_dwordx4 v[228:231], v85, s[70:71]
	global_load_dwordx4 v[232:235], v85, s[70:71] offset:64
	v_add_u32_e32 v85, 0x4000, v85
	v_add_u32_e32 v227, 0x1600, v29
	v_cvt_f32_i32_e32 v227, v227
	v_mul_f32_e32 v227, v93, v227
	v_mul_f32_e32 v227, 0x3fb8aa3b, v227
	v_exp_f32_e32 v226, v227
	s_waitcnt lgkmcnt(10)
	v_mfma_f32_16x16x32_f16 v[8:11], v[12:15], v[0:3], 0
	v_mfma_f32_16x16x32_f16 v[8:11], v[16:19], v[4:7], v[8:11]
	s_nop 7
	v_cndmask_b32_e64 v222, v8, v11, s[40:41]
	v_cndmask_b32_e64 v223, v9, v10, s[40:41]
	v_cndmask_b32_e64 v224, v10, v9, s[40:41]
	v_cndmask_b32_e64 v225, v11, v8, s[40:41]
	v_mul_f32_e32 v222, v222, v226
	v_mul_f32_e32 v223, v223, v226
	v_mul_f32_e32 v224, v224, v226
	v_mul_f32_e32 v225, v225, v226
	v_mul_f32_e32 v222, v80, v222
	v_mul_f32_e32 v223, v81, v223
	v_mul_f32_e32 v224, v82, v224
	v_mul_f32_e32 v225, v84, v225
	v_mul_f32_e32 v31, v222, v222
	v_fmac_f32_e32 v31, v223, v223
	v_fmac_f32_e32 v31, v224, v224
	v_fmac_f32_e32 v31, v225, v225
	v_add_f32_e32 v28, v28, v31
	s_mov_b64 exec, s[38:39]
	ds_write2_b32 v78, v222, v223 offset1:2
	ds_write2_b32 v78, v224, v225 offset0:4 offset1:6
	s_mov_b64 exec, -1
	v_add_u32_e32 v78, v78, v79
	s_waitcnt vmcnt(4)
	ds_bpermute_b32 v12, v30, v236
	ds_bpermute_b32 v13, v30, v237
	ds_bpermute_b32 v14, v30, v238
	ds_bpermute_b32 v15, v30, v239
	ds_bpermute_b32 v16, v30, v240
	ds_bpermute_b32 v17, v30, v241
	ds_bpermute_b32 v18, v30, v242
	ds_bpermute_b32 v19, v30, v243
	global_load_dwordx4 v[236:239], v85, s[70:71]
	global_load_dwordx4 v[240:243], v85, s[70:71] offset:64
	v_add_u32_e32 v85, 0x4000, v85
	v_add_u32_e32 v227, 0x1680, v29
	v_cvt_f32_i32_e32 v227, v227
	v_mul_f32_e32 v227, v93, v227
	v_mul_f32_e32 v227, 0x3fb8aa3b, v227
	v_exp_f32_e32 v226, v227
	s_waitcnt lgkmcnt(10)
	v_mfma_f32_16x16x32_f16 v[8:11], v[20:23], v[0:3], 0
	v_mfma_f32_16x16x32_f16 v[8:11], v[24:27], v[4:7], v[8:11]
	s_nop 7
	v_cndmask_b32_e64 v222, v8, v11, s[40:41]
	v_cndmask_b32_e64 v223, v9, v10, s[40:41]
	v_cndmask_b32_e64 v224, v10, v9, s[40:41]
	v_cndmask_b32_e64 v225, v11, v8, s[40:41]
	v_mul_f32_e32 v222, v222, v226
	v_mul_f32_e32 v223, v223, v226
	v_mul_f32_e32 v224, v224, v226
	v_mul_f32_e32 v225, v225, v226
	v_mul_f32_e32 v222, v80, v222
	v_mul_f32_e32 v223, v81, v223
	v_mul_f32_e32 v224, v82, v224
	v_mul_f32_e32 v225, v84, v225
	v_mul_f32_e32 v31, v222, v222
	v_fmac_f32_e32 v31, v223, v223
	v_fmac_f32_e32 v31, v224, v224
	v_fmac_f32_e32 v31, v225, v225
	v_add_f32_e32 v28, v28, v31
	s_mov_b64 exec, s[38:39]
	ds_write2_b32 v78, v222, v223 offset1:2
	ds_write2_b32 v78, v224, v225 offset0:4 offset1:6
	s_mov_b64 exec, -1
	v_add_u32_e32 v78, v78, v79
	s_waitcnt vmcnt(4)
	ds_bpermute_b32 v20, v30, v244
	ds_bpermute_b32 v21, v30, v245
	ds_bpermute_b32 v22, v30, v246
	ds_bpermute_b32 v23, v30, v247
	ds_bpermute_b32 v24, v30, v248
	ds_bpermute_b32 v25, v30, v249
	ds_bpermute_b32 v26, v30, v250
	ds_bpermute_b32 v27, v30, v251
	global_load_dwordx4 v[244:247], v85, s[70:71]
	global_load_dwordx4 v[248:251], v85, s[70:71] offset:64
	v_add_u32_e32 v85, 0x4000, v85
	v_add_u32_e32 v227, 0x1700, v29
	v_cvt_f32_i32_e32 v227, v227
	v_mul_f32_e32 v227, v93, v227
	v_mul_f32_e32 v227, 0x3fb8aa3b, v227
	v_exp_f32_e32 v226, v227
	s_waitcnt lgkmcnt(10)
; __device__ __forceinline__ void phase_hyena(KP kp_, int hf){ asm volatile("" : "+s"(kp_)); const Params p=load_params(kp_);
;     ...
;       _Pragma("unroll 8") for (int i=0;i<64;++i){ int tl=wid+8*i;
;         const _Float16* ap=a3+(size_t)(tl*16+n)*64+kg*8;
;         f16x8 a0=*(const f16x8*)ap, a1=*(const f16x8*)(ap+32);
;         f32x4 dd={0.f,0.f,0.f,0.f};
;         dd=__builtin_amdgcn_mfma_f32_16x16x32_f16(a0,bw0,dd,0,0,0);
;         dd=__builtin_amdgcn_mfma_f32_16x16x32_f16(a1,bw1,dd,0,0,0);
;         if (n<4){ float d0=__expf(dsc*(float)(tl*16)); int lag0=tl*16+kg*4;
;           float v0=dd[0]*d0*pj0, v1=dd[1]*d0*pj1, v2=dd[2]*d0*pj2, v3=dd[3]*d0*pj3;
;           if (!side1){ Zf[2*(lag0)+order]=v0; Zf[2*(lag0+1)+order]=v1; Zf[2*(lag0+2)+order]=v2; Zf[2*(lag0+3)+order]=v3; ssl+=v0*v0+v1*v1+v2*v2+v3*v3; }
;           else { if (lag0>=1){ Zf[2*(16384-lag0)+order]=v0; ssl+=v0*v0; }
;             Zf[2*(16384-lag0-1)+order]=v1; Zf[2*(16384-lag0-2)+order]=v2; Zf[2*(16384-lag0-3)+order]=v3; ssl+=v1*v1+v2*v2+v3*v3; } }
;       }
	v_mfma_f32_16x16x32_f16 v[8:11], v[12:15], v[0:3], 0
	v_mfma_f32_16x16x32_f16 v[8:11], v[16:19], v[4:7], v[8:11]
	s_nop 7
	v_cndmask_b32_e64 v222, v8, v11, s[40:41]
	v_cndmask_b32_e64 v223, v9, v10, s[40:41]
	v_cndmask_b32_e64 v224, v10, v9, s[40:41]
	v_cndmask_b32_e64 v225, v11, v8, s[40:41]
	v_mul_f32_e32 v222, v222, v226
	v_mul_f32_e32 v223, v223, v226
	v_mul_f32_e32 v224, v224, v226
	v_mul_f32_e32 v225, v225, v226
	v_mul_f32_e32 v222, v80, v222
	v_mul_f32_e32 v223, v81, v223
	v_mul_f32_e32 v224, v82, v224
	v_mul_f32_e32 v225, v84, v225
	v_mul_f32_e32 v31, v222, v222
	v_fmac_f32_e32 v31, v223, v223
	v_fmac_f32_e32 v31, v224, v224
	v_fmac_f32_e32 v31, v225, v225
	v_add_f32_e32 v28, v28, v31
	s_mov_b64 exec, s[38:39]
	ds_write2_b32 v78, v222, v223 offset1:2
	ds_write2_b32 v78, v224, v225 offset0:4 offset1:6
	s_mov_b64 exec, -1
	v_add_u32_e32 v78, v78, v79
	s_waitcnt vmcnt(4)
	ds_bpermute_b32 v12, v30, v228
	ds_bpermute_b32 v13, v30, v229
	ds_bpermute_b32 v14, v30, v230
	ds_bpermute_b32 v15, v30, v231
	ds_bpermute_b32 v16, v30, v232
	ds_bpermute_b32 v17, v30, v233
	ds_bpermute_b32 v18, v30, v234
	ds_bpermute_b32 v19, v30, v235
	global_load_dwordx4 v[228:231], v85, s[70:71]
	global_load_dwordx4 v[232:235], v85, s[70:71] offset:64
	v_add_u32_e32 v85, 0x4000, v85
	v_add_u32_e32 v227, 0x1780, v29
	v_cvt_f32_i32_e32 v227, v227
	v_mul_f32_e32 v227, v93, v227
	v_mul_f32_e32 v227, 0x3fb8aa3b, v227
	v_exp_f32_e32 v226, v227
	s_waitcnt lgkmcnt(10)
	v_mfma_f32_16x16x32_f16 v[8:11], v[20:23], v[0:3], 0
	v_mfma_f32_16x16x32_f16 v[8:11], v[24:27], v[4:7], v[8:11]
	s_nop 7
	v_cndmask_b32_e64 v222, v8, v11, s[40:41]
	v_cndmask_b32_e64 v223, v9, v10, s[40:41]
	v_cndmask_b32_e64 v224, v10, v9, s[40:41]
	v_cndmask_b32_e64 v225, v11, v8, s[40:41]
	v_mul_f32_e32 v222, v222, v226
	v_mul_f32_e32 v223, v223, v226
	v_mul_f32_e32 v224, v224, v226
	v_mul_f32_e32 v225, v225, v226
	v_mul_f32_e32 v222, v80, v222
	v_mul_f32_e32 v223, v81, v223
	v_mul_f32_e32 v224, v82, v224
	v_mul_f32_e32 v225, v84, v225
	v_mul_f32_e32 v31, v222, v222
	v_fmac_f32_e32 v31, v223, v223
	v_fmac_f32_e32 v31, v224, v224
	v_fmac_f32_e32 v31, v225, v225
	v_add_f32_e32 v28, v28, v31
	s_mov_b64 exec, s[38:39]
	ds_write2_b32 v78, v222, v223 offset1:2
	ds_write2_b32 v78, v224, v225 offset0:4 offset1:6
	s_mov_b64 exec, -1
	v_add_u32_e32 v78, v78, v79
	s_waitcnt vmcnt(4)
	ds_bpermute_b32 v20, v30, v236
	ds_bpermute_b32 v21, v30, v237
	ds_bpermute_b32 v22, v30, v238
	ds_bpermute_b32 v23, v30, v239
	ds_bpermute_b32 v24, v30, v240
	ds_bpermute_b32 v25, v30, v241
	ds_bpermute_b32 v26, v30, v242
	ds_bpermute_b32 v27, v30, v243
	global_load_dwordx4 v[236:239], v85, s[70:71]
	global_load_dwordx4 v[240:243], v85, s[70:71] offset:64
	v_add_u32_e32 v85, 0x4000, v85
	v_add_u32_e32 v227, 0x1800, v29
	v_cvt_f32_i32_e32 v227, v227
	v_mul_f32_e32 v227, v93, v227
	v_mul_f32_e32 v227, 0x3fb8aa3b, v227
	v_exp_f32_e32 v226, v227
	s_waitcnt lgkmcnt(10)
	v_mfma_f32_16x16x32_f16 v[8:11], v[12:15], v[0:3], 0
	v_mfma_f32_16x16x32_f16 v[8:11], v[16:19], v[4:7], v[8:11]
	s_nop 7
	v_cndmask_b32_e64 v222, v8, v11, s[40:41]
	v_cndmask_b32_e64 v223, v9, v10, s[40:41]
	v_cndmask_b32_e64 v224, v10, v9, s[40:41]
	v_cndmask_b32_e64 v225, v11, v8, s[40:41]
	v_mul_f32_e32 v222, v222, v226
	v_mul_f32_e32 v223, v223, v226
	v_mul_f32_e32 v224, v224, v226
	v_mul_f32_e32 v225, v225, v226
	v_mul_f32_e32 v222, v80, v222
	v_mul_f32_e32 v223, v81, v223
	v_mul_f32_e32 v224, v82, v224
	v_mul_f32_e32 v225, v84, v225
	v_mul_f32_e32 v31, v222, v222
	v_fmac_f32_e32 v31, v223, v223
	v_fmac_f32_e32 v31, v224, v224
	v_fmac_f32_e32 v31, v225, v225
	v_add_f32_e32 v28, v28, v31
	s_mov_b64 exec, s[38:39]
	ds_write2_b32 v78, v222, v223 offset1:2
	ds_write2_b32 v78, v224, v225 offset0:4 offset1:6
	s_mov_b64 exec, -1
	v_add_u32_e32 v78, v78, v79
	s_waitcnt vmcnt(4)
	ds_bpermute_b32 v12, v30, v244
	ds_bpermute_b32 v13, v30, v245
	ds_bpermute_b32 v14, v30, v246
	ds_bpermute_b32 v15, v30, v247
	ds_bpermute_b32 v16, v30, v248
	ds_bpermute_b32 v17, v30, v249
	ds_bpermute_b32 v18, v30, v250
	ds_bpermute_b32 v19, v30, v251
	global_load_dwordx4 v[244:247], v85, s[70:71]
	global_load_dwordx4 v[248:251], v85, s[70:71] offset:64
	v_add_u32_e32 v85, 0x4000, v85
	v_add_u32_e32 v227, 0x1880, v29
	v_cvt_f32_i32_e32 v227, v227
	v_mul_f32_e32 v227, v93, v227
	v_mul_f32_e32 v227, 0x3fb8aa3b, v227
	v_exp_f32_e32 v226, v227
	s_waitcnt lgkmcnt(10)
	v_mfma_f32_16x16x32_f16 v[8:11], v[20:23], v[0:3], 0
	v_mfma_f32_16x16x32_f16 v[8:11], v[24:27], v[4:7], v[8:11]
	s_nop 7
	v_cndmask_b32_e64 v222, v8, v11, s[40:41]
	v_cndmask_b32_e64 v223, v9, v10, s[40:41]
	v_cndmask_b32_e64 v224, v10, v9, s[40:41]
	v_cndmask_b32_e64 v225, v11, v8, s[40:41]
	v_mul_f32_e32 v222, v222, v226
	v_mul_f32_e32 v223, v223, v226
	v_mul_f32_e32 v224, v224, v226
	v_mul_f32_e32 v225, v225, v226
	v_mul_f32_e32 v222, v80, v222
	v_mul_f32_e32 v223, v81, v223
	v_mul_f32_e32 v224, v82, v224
	v_mul_f32_e32 v225, v84, v225
	v_mul_f32_e32 v31, v222, v222
	v_fmac_f32_e32 v31, v223, v223
	v_fmac_f32_e32 v31, v224, v224
	v_fmac_f32_e32 v31, v225, v225
	v_add_f32_e32 v28, v28, v31
	s_mov_b64 exec, s[38:39]
	ds_write2_b32 v78, v222, v223 offset1:2
	ds_write2_b32 v78, v224, v225 offset0:4 offset1:6
	s_mov_b64 exec, -1
	v_add_u32_e32 v78, v78, v79
	s_waitcnt vmcnt(4)
	ds_bpermute_b32 v20, v30, v228
	ds_bpermute_b32 v21, v30, v229
	ds_bpermute_b32 v22, v30, v230
	ds_bpermute_b32 v23, v30, v231
	ds_bpermute_b32 v24, v30, v232
	ds_bpermute_b32 v25, v30, v233
	ds_bpermute_b32 v26, v30, v234
	ds_bpermute_b32 v27, v30, v235
	global_load_dwordx4 v[228:231], v85, s[70:71]
	global_load_dwordx4 v[232:235], v85, s[70:71] offset:64
	v_add_u32_e32 v85, 0x4000, v85
	v_add_u32_e32 v227, 0x1900, v29
	v_cvt_f32_i32_e32 v227, v227
	v_mul_f32_e32 v227, v93, v227
	v_mul_f32_e32 v227, 0x3fb8aa3b, v227
	v_exp_f32_e32 v226, v227
	s_waitcnt lgkmcnt(10)
; __device__ __forceinline__ void phase_hyena(KP kp_, int hf){ asm volatile("" : "+s"(kp_)); const Params p=load_params(kp_);
;     ...
;       _Pragma("unroll 8") for (int i=0;i<64;++i){ int tl=wid+8*i;
;         const _Float16* ap=a3+(size_t)(tl*16+n)*64+kg*8;
;         f16x8 a0=*(const f16x8*)ap, a1=*(const f16x8*)(ap+32);
;         f32x4 dd={0.f,0.f,0.f,0.f};
;         dd=__builtin_amdgcn_mfma_f32_16x16x32_f16(a0,bw0,dd,0,0,0);
;         dd=__builtin_amdgcn_mfma_f32_16x16x32_f16(a1,bw1,dd,0,0,0);
;         if (n<4){ float d0=__expf(dsc*(float)(tl*16)); int lag0=tl*16+kg*4;
;           float v0=dd[0]*d0*pj0, v1=dd[1]*d0*pj1, v2=dd[2]*d0*pj2, v3=dd[3]*d0*pj3;
;           if (!side1){ Zf[2*(lag0)+order]=v0; Zf[2*(lag0+1)+order]=v1; Zf[2*(lag0+2)+order]=v2; Zf[2*(lag0+3)+order]=v3; ssl+=v0*v0+v1*v1+v2*v2+v3*v3; }
;           else { if (lag0>=1){ Zf[2*(16384-lag0)+order]=v0; ssl+=v0*v0; }
;             Zf[2*(16384-lag0-1)+order]=v1; Zf[2*(16384-lag0-2)+order]=v2; Zf[2*(16384-lag0-3)+order]=v3; ssl+=v1*v1+v2*v2+v3*v3; } }
;       }
	v_mfma_f32_16x16x32_f16 v[8:11], v[12:15], v[0:3], 0
	v_mfma_f32_16x16x32_f16 v[8:11], v[16:19], v[4:7], v[8:11]
	s_nop 7
	v_cndmask_b32_e64 v222, v8, v11, s[40:41]
	v_cndmask_b32_e64 v223, v9, v10, s[40:41]
	v_cndmask_b32_e64 v224, v10, v9, s[40:41]
	v_cndmask_b32_e64 v225, v11, v8, s[40:41]
	v_mul_f32_e32 v222, v222, v226
	v_mul_f32_e32 v223, v223, v226
	v_mul_f32_e32 v224, v224, v226
	v_mul_f32_e32 v225, v225, v226
	v_mul_f32_e32 v222, v80, v222
	v_mul_f32_e32 v223, v81, v223
	v_mul_f32_e32 v224, v82, v224
	v_mul_f32_e32 v225, v84, v225
	v_mul_f32_e32 v31, v222, v222
	v_fmac_f32_e32 v31, v223, v223
	v_fmac_f32_e32 v31, v224, v224
	v_fmac_f32_e32 v31, v225, v225
	v_add_f32_e32 v28, v28, v31
	s_mov_b64 exec, s[38:39]
	ds_write2_b32 v78, v222, v223 offset1:2
	ds_write2_b32 v78, v224, v225 offset0:4 offset1:6
	s_mov_b64 exec, -1
	v_add_u32_e32 v78, v78, v79
	s_waitcnt vmcnt(4)
	ds_bpermute_b32 v12, v30, v236
	ds_bpermute_b32 v13, v30, v237
	ds_bpermute_b32 v14, v30, v238
	ds_bpermute_b32 v15, v30, v239
	ds_bpermute_b32 v16, v30, v240
	ds_bpermute_b32 v17, v30, v241
	ds_bpermute_b32 v18, v30, v242
	ds_bpermute_b32 v19, v30, v243
	global_load_dwordx4 v[236:239], v85, s[70:71]
	global_load_dwordx4 v[240:243], v85, s[70:71] offset:64
	v_add_u32_e32 v85, 0x4000, v85
	v_add_u32_e32 v227, 0x1980, v29
	v_cvt_f32_i32_e32 v227, v227
	v_mul_f32_e32 v227, v93, v227
	v_mul_f32_e32 v227, 0x3fb8aa3b, v227
	v_exp_f32_e32 v226, v227
	s_waitcnt lgkmcnt(10)
	v_mfma_f32_16x16x32_f16 v[8:11], v[20:23], v[0:3], 0
	v_mfma_f32_16x16x32_f16 v[8:11], v[24:27], v[4:7], v[8:11]
	s_nop 7
	v_cndmask_b32_e64 v222, v8, v11, s[40:41]
	v_cndmask_b32_e64 v223, v9, v10, s[40:41]
	v_cndmask_b32_e64 v224, v10, v9, s[40:41]
	v_cndmask_b32_e64 v225, v11, v8, s[40:41]
	v_mul_f32_e32 v222, v222, v226
	v_mul_f32_e32 v223, v223, v226
	v_mul_f32_e32 v224, v224, v226
	v_mul_f32_e32 v225, v225, v226
	v_mul_f32_e32 v222, v80, v222
	v_mul_f32_e32 v223, v81, v223
	v_mul_f32_e32 v224, v82, v224
	v_mul_f32_e32 v225, v84, v225
	v_mul_f32_e32 v31, v222, v222
	v_fmac_f32_e32 v31, v223, v223
	v_fmac_f32_e32 v31, v224, v224
	v_fmac_f32_e32 v31, v225, v225
	v_add_f32_e32 v28, v28, v31
	s_mov_b64 exec, s[38:39]
	ds_write2_b32 v78, v222, v223 offset1:2
	ds_write2_b32 v78, v224, v225 offset0:4 offset1:6
	s_mov_b64 exec, -1
	v_add_u32_e32 v78, v78, v79
	s_waitcnt vmcnt(4)
	ds_bpermute_b32 v20, v30, v244
	ds_bpermute_b32 v21, v30, v245
	ds_bpermute_b32 v22, v30, v246
	ds_bpermute_b32 v23, v30, v247
	ds_bpermute_b32 v24, v30, v248
	ds_bpermute_b32 v25, v30, v249
	ds_bpermute_b32 v26, v30, v250
	ds_bpermute_b32 v27, v30, v251
	global_load_dwordx4 v[244:247], v85, s[70:71]
	global_load_dwordx4 v[248:251], v85, s[70:71] offset:64
	v_add_u32_e32 v85, 0x4000, v85
	v_add_u32_e32 v227, 0x1a00, v29
	v_cvt_f32_i32_e32 v227, v227
	v_mul_f32_e32 v227, v93, v227
	v_mul_f32_e32 v227, 0x3fb8aa3b, v227
	v_exp_f32_e32 v226, v227
	s_waitcnt lgkmcnt(10)
	v_mfma_f32_16x16x32_f16 v[8:11], v[12:15], v[0:3], 0
	v_mfma_f32_16x16x32_f16 v[8:11], v[16:19], v[4:7], v[8:11]
	s_nop 7
	v_cndmask_b32_e64 v222, v8, v11, s[40:41]
	v_cndmask_b32_e64 v223, v9, v10, s[40:41]
	v_cndmask_b32_e64 v224, v10, v9, s[40:41]
	v_cndmask_b32_e64 v225, v11, v8, s[40:41]
	v_mul_f32_e32 v222, v222, v226
	v_mul_f32_e32 v223, v223, v226
	v_mul_f32_e32 v224, v224, v226
	v_mul_f32_e32 v225, v225, v226
	v_mul_f32_e32 v222, v80, v222
	v_mul_f32_e32 v223, v81, v223
	v_mul_f32_e32 v224, v82, v224
	v_mul_f32_e32 v225, v84, v225
	v_mul_f32_e32 v31, v222, v222
	v_fmac_f32_e32 v31, v223, v223
	v_fmac_f32_e32 v31, v224, v224
	v_fmac_f32_e32 v31, v225, v225
	v_add_f32_e32 v28, v28, v31
	s_mov_b64 exec, s[38:39]
	ds_write2_b32 v78, v222, v223 offset1:2
	ds_write2_b32 v78, v224, v225 offset0:4 offset1:6
	s_mov_b64 exec, -1
	v_add_u32_e32 v78, v78, v79
	s_waitcnt vmcnt(4)
	ds_bpermute_b32 v12, v30, v228
	ds_bpermute_b32 v13, v30, v229
	ds_bpermute_b32 v14, v30, v230
	ds_bpermute_b32 v15, v30, v231
	ds_bpermute_b32 v16, v30, v232
	ds_bpermute_b32 v17, v30, v233
	ds_bpermute_b32 v18, v30, v234
	ds_bpermute_b32 v19, v30, v235
	global_load_dwordx4 v[228:231], v85, s[70:71]
	global_load_dwordx4 v[232:235], v85, s[70:71] offset:64
	v_add_u32_e32 v85, 0x4000, v85
	v_add_u32_e32 v227, 0x1a80, v29
	v_cvt_f32_i32_e32 v227, v227
	v_mul_f32_e32 v227, v93, v227
	v_mul_f32_e32 v227, 0x3fb8aa3b, v227
	v_exp_f32_e32 v226, v227
	s_waitcnt lgkmcnt(10)
	v_mfma_f32_16x16x32_f16 v[8:11], v[20:23], v[0:3], 0
	v_mfma_f32_16x16x32_f16 v[8:11], v[24:27], v[4:7], v[8:11]
	s_nop 7
	v_cndmask_b32_e64 v222, v8, v11, s[40:41]
	v_cndmask_b32_e64 v223, v9, v10, s[40:41]
	v_cndmask_b32_e64 v224, v10, v9, s[40:41]
	v_cndmask_b32_e64 v225, v11, v8, s[40:41]
	v_mul_f32_e32 v222, v222, v226
	v_mul_f32_e32 v223, v223, v226
	v_mul_f32_e32 v224, v224, v226
	v_mul_f32_e32 v225, v225, v226
	v_mul_f32_e32 v222, v80, v222
	v_mul_f32_e32 v223, v81, v223
	v_mul_f32_e32 v224, v82, v224
	v_mul_f32_e32 v225, v84, v225
	v_mul_f32_e32 v31, v222, v222
	v_fmac_f32_e32 v31, v223, v223
	v_fmac_f32_e32 v31, v224, v224
	v_fmac_f32_e32 v31, v225, v225
	v_add_f32_e32 v28, v28, v31
	s_mov_b64 exec, s[38:39]
	ds_write2_b32 v78, v222, v223 offset1:2
	ds_write2_b32 v78, v224, v225 offset0:4 offset1:6
	s_mov_b64 exec, -1
	v_add_u32_e32 v78, v78, v79
	s_waitcnt vmcnt(4)
	ds_bpermute_b32 v20, v30, v236
	ds_bpermute_b32 v21, v30, v237
	ds_bpermute_b32 v22, v30, v238
	ds_bpermute_b32 v23, v30, v239
	ds_bpermute_b32 v24, v30, v240
	ds_bpermute_b32 v25, v30, v241
	ds_bpermute_b32 v26, v30, v242
	ds_bpermute_b32 v27, v30, v243
	global_load_dwordx4 v[236:239], v85, s[70:71]
	global_load_dwordx4 v[240:243], v85, s[70:71] offset:64
	v_add_u32_e32 v85, 0x4000, v85
	v_add_u32_e32 v227, 0x1b00, v29
	v_cvt_f32_i32_e32 v227, v227
	v_mul_f32_e32 v227, v93, v227
	v_mul_f32_e32 v227, 0x3fb8aa3b, v227
	v_exp_f32_e32 v226, v227
	s_waitcnt lgkmcnt(10)
; __device__ __forceinline__ void phase_hyena(KP kp_, int hf){ asm volatile("" : "+s"(kp_)); const Params p=load_params(kp_);
;     ...
;       _Pragma("unroll 8") for (int i=0;i<64;++i){ int tl=wid+8*i;
;         const _Float16* ap=a3+(size_t)(tl*16+n)*64+kg*8;
;         f16x8 a0=*(const f16x8*)ap, a1=*(const f16x8*)(ap+32);
;         f32x4 dd={0.f,0.f,0.f,0.f};
;         dd=__builtin_amdgcn_mfma_f32_16x16x32_f16(a0,bw0,dd,0,0,0);
;         dd=__builtin_amdgcn_mfma_f32_16x16x32_f16(a1,bw1,dd,0,0,0);
;         if (n<4){ float d0=__expf(dsc*(float)(tl*16)); int lag0=tl*16+kg*4;
;           float v0=dd[0]*d0*pj0, v1=dd[1]*d0*pj1, v2=dd[2]*d0*pj2, v3=dd[3]*d0*pj3;
;           if (!side1){ Zf[2*(lag0)+order]=v0; Zf[2*(lag0+1)+order]=v1; Zf[2*(lag0+2)+order]=v2; Zf[2*(lag0+3)+order]=v3; ssl+=v0*v0+v1*v1+v2*v2+v3*v3; }
;           else { if (lag0>=1){ Zf[2*(16384-lag0)+order]=v0; ssl+=v0*v0; }
;             Zf[2*(16384-lag0-1)+order]=v1; Zf[2*(16384-lag0-2)+order]=v2; Zf[2*(16384-lag0-3)+order]=v3; ssl+=v1*v1+v2*v2+v3*v3; } }
;       }
	v_mfma_f32_16x16x32_f16 v[8:11], v[12:15], v[0:3], 0
	v_mfma_f32_16x16x32_f16 v[8:11], v[16:19], v[4:7], v[8:11]
	s_nop 7
	v_cndmask_b32_e64 v222, v8, v11, s[40:41]
	v_cndmask_b32_e64 v223, v9, v10, s[40:41]
	v_cndmask_b32_e64 v224, v10, v9, s[40:41]
	v_cndmask_b32_e64 v225, v11, v8, s[40:41]
	v_mul_f32_e32 v222, v222, v226
	v_mul_f32_e32 v223, v223, v226
	v_mul_f32_e32 v224, v224, v226
	v_mul_f32_e32 v225, v225, v226
	v_mul_f32_e32 v222, v80, v222
	v_mul_f32_e32 v223, v81, v223
	v_mul_f32_e32 v224, v82, v224
	v_mul_f32_e32 v225, v84, v225
	v_mul_f32_e32 v31, v222, v222
	v_fmac_f32_e32 v31, v223, v223
	v_fmac_f32_e32 v31, v224, v224
	v_fmac_f32_e32 v31, v225, v225
	v_add_f32_e32 v28, v28, v31
	s_mov_b64 exec, s[38:39]
	ds_write2_b32 v78, v222, v223 offset1:2
	ds_write2_b32 v78, v224, v225 offset0:4 offset1:6
	s_mov_b64 exec, -1
	v_add_u32_e32 v78, v78, v79
	s_waitcnt vmcnt(4)
	ds_bpermute_b32 v12, v30, v244
	ds_bpermute_b32 v13, v30, v245
	ds_bpermute_b32 v14, v30, v246
	ds_bpermute_b32 v15, v30, v247
	ds_bpermute_b32 v16, v30, v248
	ds_bpermute_b32 v17, v30, v249
	ds_bpermute_b32 v18, v30, v250
	ds_bpermute_b32 v19, v30, v251
	global_load_dwordx4 v[244:247], v85, s[70:71]
	global_load_dwordx4 v[248:251], v85, s[70:71] offset:64
	v_add_u32_e32 v85, 0x4000, v85
	v_add_u32_e32 v227, 0x1b80, v29
	v_cvt_f32_i32_e32 v227, v227
	v_mul_f32_e32 v227, v93, v227
	v_mul_f32_e32 v227, 0x3fb8aa3b, v227
	v_exp_f32_e32 v226, v227
	s_waitcnt lgkmcnt(10)
	v_mfma_f32_16x16x32_f16 v[8:11], v[20:23], v[0:3], 0
	v_mfma_f32_16x16x32_f16 v[8:11], v[24:27], v[4:7], v[8:11]
	s_nop 7
	v_cndmask_b32_e64 v222, v8, v11, s[40:41]
	v_cndmask_b32_e64 v223, v9, v10, s[40:41]
	v_cndmask_b32_e64 v224, v10, v9, s[40:41]
	v_cndmask_b32_e64 v225, v11, v8, s[40:41]
	v_mul_f32_e32 v222, v222, v226
	v_mul_f32_e32 v223, v223, v226
	v_mul_f32_e32 v224, v224, v226
	v_mul_f32_e32 v225, v225, v226
	v_mul_f32_e32 v222, v80, v222
	v_mul_f32_e32 v223, v81, v223
	v_mul_f32_e32 v224, v82, v224
	v_mul_f32_e32 v225, v84, v225
	v_mul_f32_e32 v31, v222, v222
	v_fmac_f32_e32 v31, v223, v223
	v_fmac_f32_e32 v31, v224, v224
	v_fmac_f32_e32 v31, v225, v225
	v_add_f32_e32 v28, v28, v31
	s_mov_b64 exec, s[38:39]
	ds_write2_b32 v78, v222, v223 offset1:2
	ds_write2_b32 v78, v224, v225 offset0:4 offset1:6
	s_mov_b64 exec, -1
	v_add_u32_e32 v78, v78, v79
	s_waitcnt vmcnt(4)
	ds_bpermute_b32 v20, v30, v228
	ds_bpermute_b32 v21, v30, v229
	ds_bpermute_b32 v22, v30, v230
	ds_bpermute_b32 v23, v30, v231
	ds_bpermute_b32 v24, v30, v232
	ds_bpermute_b32 v25, v30, v233
	ds_bpermute_b32 v26, v30, v234
	ds_bpermute_b32 v27, v30, v235
	global_load_dwordx4 v[228:231], v85, s[70:71]
	global_load_dwordx4 v[232:235], v85, s[70:71] offset:64
	v_add_u32_e32 v85, 0x4000, v85
	v_add_u32_e32 v227, 0x1c00, v29
	v_cvt_f32_i32_e32 v227, v227
	v_mul_f32_e32 v227, v93, v227
	v_mul_f32_e32 v227, 0x3fb8aa3b, v227
	v_exp_f32_e32 v226, v227
	s_waitcnt lgkmcnt(10)
	v_mfma_f32_16x16x32_f16 v[8:11], v[12:15], v[0:3], 0
	v_mfma_f32_16x16x32_f16 v[8:11], v[16:19], v[4:7], v[8:11]
	s_nop 7
	v_cndmask_b32_e64 v222, v8, v11, s[40:41]
	v_cndmask_b32_e64 v223, v9, v10, s[40:41]
	v_cndmask_b32_e64 v224, v10, v9, s[40:41]
	v_cndmask_b32_e64 v225, v11, v8, s[40:41]
	v_mul_f32_e32 v222, v222, v226
	v_mul_f32_e32 v223, v223, v226
	v_mul_f32_e32 v224, v224, v226
	v_mul_f32_e32 v225, v225, v226
	v_mul_f32_e32 v222, v80, v222
	v_mul_f32_e32 v223, v81, v223
	v_mul_f32_e32 v224, v82, v224
	v_mul_f32_e32 v225, v84, v225
	v_mul_f32_e32 v31, v222, v222
	v_fmac_f32_e32 v31, v223, v223
	v_fmac_f32_e32 v31, v224, v224
	v_fmac_f32_e32 v31, v225, v225
	v_add_f32_e32 v28, v28, v31
	s_mov_b64 exec, s[38:39]
	ds_write2_b32 v78, v222, v223 offset1:2
	ds_write2_b32 v78, v224, v225 offset0:4 offset1:6
	s_mov_b64 exec, -1
	v_add_u32_e32 v78, v78, v79
	s_waitcnt vmcnt(4)
	ds_bpermute_b32 v12, v30, v236
	ds_bpermute_b32 v13, v30, v237
	ds_bpermute_b32 v14, v30, v238
	ds_bpermute_b32 v15, v30, v239
	ds_bpermute_b32 v16, v30, v240
	ds_bpermute_b32 v17, v30, v241
	ds_bpermute_b32 v18, v30, v242
	ds_bpermute_b32 v19, v30, v243
	global_load_dwordx4 v[236:239], v85, s[70:71]
	global_load_dwordx4 v[240:243], v85, s[70:71] offset:64
	v_add_u32_e32 v85, 0x4000, v85
	v_add_u32_e32 v227, 0x1c80, v29
	v_cvt_f32_i32_e32 v227, v227
	v_mul_f32_e32 v227, v93, v227
	v_mul_f32_e32 v227, 0x3fb8aa3b, v227
	v_exp_f32_e32 v226, v227
	s_waitcnt lgkmcnt(10)
	v_mfma_f32_16x16x32_f16 v[8:11], v[20:23], v[0:3], 0
	v_mfma_f32_16x16x32_f16 v[8:11], v[24:27], v[4:7], v[8:11]
	s_nop 7
	v_cndmask_b32_e64 v222, v8, v11, s[40:41]
	v_cndmask_b32_e64 v223, v9, v10, s[40:41]
	v_cndmask_b32_e64 v224, v10, v9, s[40:41]
	v_cndmask_b32_e64 v225, v11, v8, s[40:41]
	v_mul_f32_e32 v222, v222, v226
	v_mul_f32_e32 v223, v223, v226
	v_mul_f32_e32 v224, v224, v226
	v_mul_f32_e32 v225, v225, v226
	v_mul_f32_e32 v222, v80, v222
	v_mul_f32_e32 v223, v81, v223
	v_mul_f32_e32 v224, v82, v224
	v_mul_f32_e32 v225, v84, v225
	v_mul_f32_e32 v31, v222, v222
	v_fmac_f32_e32 v31, v223, v223
	v_fmac_f32_e32 v31, v224, v224
	v_fmac_f32_e32 v31, v225, v225
	v_add_f32_e32 v28, v28, v31
	s_mov_b64 exec, s[38:39]
	ds_write2_b32 v78, v222, v223 offset1:2
	ds_write2_b32 v78, v224, v225 offset0:4 offset1:6
	s_mov_b64 exec, -1
	v_add_u32_e32 v78, v78, v79
	s_waitcnt vmcnt(4)
	ds_bpermute_b32 v20, v30, v244
	ds_bpermute_b32 v21, v30, v245
	ds_bpermute_b32 v22, v30, v246
	ds_bpermute_b32 v23, v30, v247
	ds_bpermute_b32 v24, v30, v248
	ds_bpermute_b32 v25, v30, v249
	ds_bpermute_b32 v26, v30, v250
	ds_bpermute_b32 v27, v30, v251
	global_load_dwordx4 v[244:247], v85, s[70:71]
	global_load_dwordx4 v[248:251], v85, s[70:71] offset:64
	v_add_u32_e32 v85, 0x4000, v85
	v_add_u32_e32 v227, 0x1d00, v29
	v_cvt_f32_i32_e32 v227, v227
	v_mul_f32_e32 v227, v93, v227
	v_mul_f32_e32 v227, 0x3fb8aa3b, v227
	v_exp_f32_e32 v226, v227
	s_waitcnt lgkmcnt(10)
; __device__ __forceinline__ void phase_hyena(KP kp_, int hf){ asm volatile("" : "+s"(kp_)); const Params p=load_params(kp_);
;     ...
;       _Pragma("unroll 8") for (int i=0;i<64;++i){ int tl=wid+8*i;
;         const _Float16* ap=a3+(size_t)(tl*16+n)*64+kg*8;
;         f16x8 a0=*(const f16x8*)ap, a1=*(const f16x8*)(ap+32);
;         f32x4 dd={0.f,0.f,0.f,0.f};
;         dd=__builtin_amdgcn_mfma_f32_16x16x32_f16(a0,bw0,dd,0,0,0);
;         dd=__builtin_amdgcn_mfma_f32_16x16x32_f16(a1,bw1,dd,0,0,0);
;         if (n<4){ float d0=__expf(dsc*(float)(tl*16)); int lag0=tl*16+kg*4;
;           float v0=dd[0]*d0*pj0, v1=dd[1]*d0*pj1, v2=dd[2]*d0*pj2, v3=dd[3]*d0*pj3;
;           if (!side1){ Zf[2*(lag0)+order]=v0; Zf[2*(lag0+1)+order]=v1; Zf[2*(lag0+2)+order]=v2; Zf[2*(lag0+3)+order]=v3; ssl+=v0*v0+v1*v1+v2*v2+v3*v3; }
;           else { if (lag0>=1){ Zf[2*(16384-lag0)+order]=v0; ssl+=v0*v0; }
;             Zf[2*(16384-lag0-1)+order]=v1; Zf[2*(16384-lag0-2)+order]=v2; Zf[2*(16384-lag0-3)+order]=v3; ssl+=v1*v1+v2*v2+v3*v3; } }
;       }
	v_mfma_f32_16x16x32_f16 v[8:11], v[12:15], v[0:3], 0
	v_mfma_f32_16x16x32_f16 v[8:11], v[16:19], v[4:7], v[8:11]
	s_nop 7
	v_cndmask_b32_e64 v222, v8, v11, s[40:41]
	v_cndmask_b32_e64 v223, v9, v10, s[40:41]
	v_cndmask_b32_e64 v224, v10, v9, s[40:41]
	v_cndmask_b32_e64 v225, v11, v8, s[40:41]
	v_mul_f32_e32 v222, v222, v226
	v_mul_f32_e32 v223, v223, v226
	v_mul_f32_e32 v224, v224, v226
	v_mul_f32_e32 v225, v225, v226
	v_mul_f32_e32 v222, v80, v222
	v_mul_f32_e32 v223, v81, v223
	v_mul_f32_e32 v224, v82, v224
	v_mul_f32_e32 v225, v84, v225
	v_mul_f32_e32 v31, v222, v222
	v_fmac_f32_e32 v31, v223, v223
	v_fmac_f32_e32 v31, v224, v224
	v_fmac_f32_e32 v31, v225, v225
	v_add_f32_e32 v28, v28, v31
	s_mov_b64 exec, s[38:39]
	ds_write2_b32 v78, v222, v223 offset1:2
	ds_write2_b32 v78, v224, v225 offset0:4 offset1:6
	s_mov_b64 exec, -1
	v_add_u32_e32 v78, v78, v79
	s_waitcnt vmcnt(4)
	ds_bpermute_b32 v12, v30, v228
	ds_bpermute_b32 v13, v30, v229
	ds_bpermute_b32 v14, v30, v230
	ds_bpermute_b32 v15, v30, v231
	ds_bpermute_b32 v16, v30, v232
	ds_bpermute_b32 v17, v30, v233
	ds_bpermute_b32 v18, v30, v234
	ds_bpermute_b32 v19, v30, v235
	global_load_dwordx4 v[228:231], v85, s[70:71]
	global_load_dwordx4 v[232:235], v85, s[70:71] offset:64
	v_add_u32_e32 v85, 0x4000, v85
	v_add_u32_e32 v227, 0x1d80, v29
	v_cvt_f32_i32_e32 v227, v227
	v_mul_f32_e32 v227, v93, v227
	v_mul_f32_e32 v227, 0x3fb8aa3b, v227
	v_exp_f32_e32 v226, v227
	s_waitcnt lgkmcnt(10)
	v_mfma_f32_16x16x32_f16 v[8:11], v[20:23], v[0:3], 0
	v_mfma_f32_16x16x32_f16 v[8:11], v[24:27], v[4:7], v[8:11]
	s_nop 7
	v_cndmask_b32_e64 v222, v8, v11, s[40:41]
	v_cndmask_b32_e64 v223, v9, v10, s[40:41]
	v_cndmask_b32_e64 v224, v10, v9, s[40:41]
	v_cndmask_b32_e64 v225, v11, v8, s[40:41]
	v_mul_f32_e32 v222, v222, v226
	v_mul_f32_e32 v223, v223, v226
	v_mul_f32_e32 v224, v224, v226
	v_mul_f32_e32 v225, v225, v226
	v_mul_f32_e32 v222, v80, v222
	v_mul_f32_e32 v223, v81, v223
	v_mul_f32_e32 v224, v82, v224
	v_mul_f32_e32 v225, v84, v225
	v_mul_f32_e32 v31, v222, v222
	v_fmac_f32_e32 v31, v223, v223
	v_fmac_f32_e32 v31, v224, v224
	v_fmac_f32_e32 v31, v225, v225
	v_add_f32_e32 v28, v28, v31
	s_mov_b64 exec, s[38:39]
	ds_write2_b32 v78, v222, v223 offset1:2
	ds_write2_b32 v78, v224, v225 offset0:4 offset1:6
	s_mov_b64 exec, -1
	v_add_u32_e32 v78, v78, v79
	s_waitcnt vmcnt(4)
	ds_bpermute_b32 v20, v30, v236
	ds_bpermute_b32 v21, v30, v237
	ds_bpermute_b32 v22, v30, v238
	ds_bpermute_b32 v23, v30, v239
	ds_bpermute_b32 v24, v30, v240
	ds_bpermute_b32 v25, v30, v241
	ds_bpermute_b32 v26, v30, v242
	ds_bpermute_b32 v27, v30, v243
	v_add_u32_e32 v227, 0x1e00, v29
	v_cvt_f32_i32_e32 v227, v227
	v_mul_f32_e32 v227, v93, v227
	v_mul_f32_e32 v227, 0x3fb8aa3b, v227
	v_exp_f32_e32 v226, v227
	s_waitcnt lgkmcnt(10)
	v_mfma_f32_16x16x32_f16 v[8:11], v[12:15], v[0:3], 0
	v_mfma_f32_16x16x32_f16 v[8:11], v[16:19], v[4:7], v[8:11]
	s_nop 7
	v_cndmask_b32_e64 v222, v8, v11, s[40:41]
	v_cndmask_b32_e64 v223, v9, v10, s[40:41]
	v_cndmask_b32_e64 v224, v10, v9, s[40:41]
	v_cndmask_b32_e64 v225, v11, v8, s[40:41]
	v_mul_f32_e32 v222, v222, v226
	v_mul_f32_e32 v223, v223, v226
	v_mul_f32_e32 v224, v224, v226
	v_mul_f32_e32 v225, v225, v226
	v_mul_f32_e32 v222, v80, v222
	v_mul_f32_e32 v223, v81, v223
	v_mul_f32_e32 v224, v82, v224
	v_mul_f32_e32 v225, v84, v225
	v_mul_f32_e32 v31, v222, v222
	v_fmac_f32_e32 v31, v223, v223
	v_fmac_f32_e32 v31, v224, v224
	v_fmac_f32_e32 v31, v225, v225
	v_add_f32_e32 v28, v28, v31
	s_mov_b64 exec, s[38:39]
	ds_write2_b32 v78, v222, v223 offset1:2
	ds_write2_b32 v78, v224, v225 offset0:4 offset1:6
	s_mov_b64 exec, -1
	v_add_u32_e32 v78, v78, v79
	s_waitcnt vmcnt(2)
; __device__ __forceinline__ void phase_hyena(KP kp_, int hf){ asm volatile("" : "+s"(kp_)); const Params p=load_params(kp_);
;     ...
;       _Pragma("unroll 8") for (int i=0;i<64;++i){ int tl=wid+8*i;
;         const _Float16* ap=a3+(size_t)(tl*16+n)*64+kg*8;
;         f16x8 a0=*(const f16x8*)ap, a1=*(const f16x8*)(ap+32);
;         f32x4 dd={0.f,0.f,0.f,0.f};
;         dd=__builtin_amdgcn_mfma_f32_16x16x32_f16(a0,bw0,dd,0,0,0);
;         dd=__builtin_amdgcn_mfma_f32_16x16x32_f16(a1,bw1,dd,0,0,0);
;         if (n<4){ float d0=__expf(dsc*(float)(tl*16)); int lag0=tl*16+kg*4;
;           float v0=dd[0]*d0*pj0, v1=dd[1]*d0*pj1, v2=dd[2]*d0*pj2, v3=dd[3]*d0*pj3;
;           if (!side1){ Zf[2*(lag0)+order]=v0; Zf[2*(lag0+1)+order]=v1; Zf[2*(lag0+2)+order]=v2; Zf[2*(lag0+3)+order]=v3; ssl+=v0*v0+v1*v1+v2*v2+v3*v3; }
;           else { if (lag0>=1){ Zf[2*(16384-lag0)+order]=v0; ssl+=v0*v0; }
;             Zf[2*(16384-lag0-1)+order]=v1; Zf[2*(16384-lag0-2)+order]=v2; Zf[2*(16384-lag0-3)+order]=v3; ssl+=v1*v1+v2*v2+v3*v3; } }
;       }
;       ss0=(n<4 && order==0)?ssl:0.f; ss1=(n<4 && order==1)?ssl:0.f;
;     }
;     if (tid==0) Z[8192]=make_float2(0.f,0.f);
	ds_bpermute_b32 v12, v30, v244
	ds_bpermute_b32 v13, v30, v245
	ds_bpermute_b32 v14, v30, v246
	ds_bpermute_b32 v15, v30, v247
	ds_bpermute_b32 v16, v30, v248
	ds_bpermute_b32 v17, v30, v249
	ds_bpermute_b32 v18, v30, v250
	ds_bpermute_b32 v19, v30, v251
	v_add_u32_e32 v227, 0x1e80, v29
	v_cvt_f32_i32_e32 v227, v227
	v_mul_f32_e32 v227, v93, v227
	v_mul_f32_e32 v227, 0x3fb8aa3b, v227
	v_exp_f32_e32 v226, v227
	s_waitcnt lgkmcnt(10)
	v_mfma_f32_16x16x32_f16 v[8:11], v[20:23], v[0:3], 0
	v_mfma_f32_16x16x32_f16 v[8:11], v[24:27], v[4:7], v[8:11]
	s_nop 7
	v_cndmask_b32_e64 v222, v8, v11, s[40:41]
	v_cndmask_b32_e64 v223, v9, v10, s[40:41]
	v_cndmask_b32_e64 v224, v10, v9, s[40:41]
	v_cndmask_b32_e64 v225, v11, v8, s[40:41]
	v_mul_f32_e32 v222, v222, v226
	v_mul_f32_e32 v223, v223, v226
	v_mul_f32_e32 v224, v224, v226
	v_mul_f32_e32 v225, v225, v226
	v_mul_f32_e32 v222, v80, v222
	v_mul_f32_e32 v223, v81, v223
	v_mul_f32_e32 v224, v82, v224
	v_mul_f32_e32 v225, v84, v225
	v_mul_f32_e32 v31, v222, v222
	v_fmac_f32_e32 v31, v223, v223
	v_fmac_f32_e32 v31, v224, v224
	v_fmac_f32_e32 v31, v225, v225
	v_add_f32_e32 v28, v28, v31
	s_mov_b64 exec, s[38:39]
	ds_write2_b32 v78, v222, v223 offset1:2
	ds_write2_b32 v78, v224, v225 offset0:4 offset1:6
	s_mov_b64 exec, -1
	v_add_u32_e32 v78, v78, v79
	s_waitcnt vmcnt(0)
	ds_bpermute_b32 v20, v30, v228
	ds_bpermute_b32 v21, v30, v229
	ds_bpermute_b32 v22, v30, v230
	ds_bpermute_b32 v23, v30, v231
	ds_bpermute_b32 v24, v30, v232
	ds_bpermute_b32 v25, v30, v233
	ds_bpermute_b32 v26, v30, v234
	ds_bpermute_b32 v27, v30, v235
	v_add_u32_e32 v227, 0x1f00, v29
	v_cvt_f32_i32_e32 v227, v227
	v_mul_f32_e32 v227, v93, v227
	v_mul_f32_e32 v227, 0x3fb8aa3b, v227
	v_exp_f32_e32 v226, v227
	s_waitcnt lgkmcnt(10)
	v_mfma_f32_16x16x32_f16 v[8:11], v[12:15], v[0:3], 0
	v_mfma_f32_16x16x32_f16 v[8:11], v[16:19], v[4:7], v[8:11]
	s_nop 7
	v_cndmask_b32_e64 v222, v8, v11, s[40:41]
	v_cndmask_b32_e64 v223, v9, v10, s[40:41]
	v_cndmask_b32_e64 v224, v10, v9, s[40:41]
	v_cndmask_b32_e64 v225, v11, v8, s[40:41]
	v_mul_f32_e32 v222, v222, v226
	v_mul_f32_e32 v223, v223, v226
	v_mul_f32_e32 v224, v224, v226
	v_mul_f32_e32 v225, v225, v226
	v_mul_f32_e32 v222, v80, v222
	v_mul_f32_e32 v223, v81, v223
	v_mul_f32_e32 v224, v82, v224
	v_mul_f32_e32 v225, v84, v225
	v_mul_f32_e32 v31, v222, v222
	v_fmac_f32_e32 v31, v223, v223
	v_fmac_f32_e32 v31, v224, v224
	v_fmac_f32_e32 v31, v225, v225
	v_add_f32_e32 v28, v28, v31
	s_mov_b64 exec, s[38:39]
	ds_write2_b32 v78, v222, v223 offset1:2
	ds_write2_b32 v78, v224, v225 offset0:4 offset1:6
	s_mov_b64 exec, -1
	v_add_u32_e32 v78, v78, v79
	v_add_u32_e32 v227, 0x1f80, v29
	v_cvt_f32_i32_e32 v227, v227
	v_mul_f32_e32 v227, v93, v227
	v_mul_f32_e32 v227, 0x3fb8aa3b, v227
	v_exp_f32_e32 v226, v227
	s_waitcnt lgkmcnt(2)
	v_mfma_f32_16x16x32_f16 v[8:11], v[20:23], v[0:3], 0
	v_mfma_f32_16x16x32_f16 v[8:11], v[24:27], v[4:7], v[8:11]
	s_nop 7
	v_cndmask_b32_e64 v222, v8, v11, s[40:41]
	v_cndmask_b32_e64 v223, v9, v10, s[40:41]
	v_cndmask_b32_e64 v224, v10, v9, s[40:41]
	v_cndmask_b32_e64 v225, v11, v8, s[40:41]
	v_mul_f32_e32 v222, v222, v226
	v_mul_f32_e32 v223, v223, v226
	v_mul_f32_e32 v224, v224, v226
	v_mul_f32_e32 v225, v225, v226
	v_mul_f32_e32 v222, v80, v222
	v_mul_f32_e32 v223, v81, v223
	v_mul_f32_e32 v224, v82, v224
	v_mul_f32_e32 v225, v84, v225
	v_mul_f32_e32 v31, v222, v222
	v_fmac_f32_e32 v31, v223, v223
	v_fmac_f32_e32 v31, v224, v224
	v_fmac_f32_e32 v31, v225, v225
	v_add_f32_e32 v28, v28, v31
	s_mov_b64 exec, s[38:39]
	ds_write2_b32 v78, v222, v223 offset1:2
	ds_write2_b32 v78, v224, v225 offset0:4 offset1:6
	s_mov_b64 exec, -1
	v_add_u32_e32 v78, v78, v79
	s_waitcnt lgkmcnt(0)
	s_and_saveexec_b64 s[12:13], s[46:47]
	s_cbranch_execz .LBB0_1316
	v_readlane_b32 s18, v253, 23
	s_nop 1
	v_mov_b32_e32 v0, s18
	ds_write_b64 v0, v[220:221]
